# P4b: 2 of 4 sample sequences run on the branch-B workgroups behind their weight copies (after the prompt scan has finished)
# baseline (speedup 1.0000x reference)
; #define LDSBAR() do { asm volatile("s_waitcnt lgkmcnt(0)" ::: "memory"); __builtin_amdgcn_s_barrier(); asm volatile("" ::: "memory"); } while (0)
; #define HG_STORE(R, s) do { LAS unsigned char* d_ = ring + (s) * HG_SLOT; *(LAS v4u*)(d_ + 16 * tid) = R.q; if (vload) *(LAS v4u*)(d_ + 16384 + 16 * tid) = R.v; *(LAS v4u*)(d_ + 8192 + 16 * tid) = R.l0; \
;         if (tid < 160) *(LAS v4u*)(d_ + 24576 + 16 * tid) = R.l1; } while (0)
; __device__ __forceinline__ void hg_seq(const Frame& F, unsigned char* ws, const float* s0, float* sout, float* Og, int seq, bool sample, int vs_base, int nvs) {
;     ...
;     if (sample && active) {
; #pragma unroll
;         for (int kb = 0; kb < 8; ++kb)
; #pragma unroll
;             for (int i = 0; i < 4; ++i) S[kb][i] = s0[((size_t)seq * 128 + 16 * kb + 4 * q + i) * 128 + 16 * vs + r];
;     } else {
; #pragma unroll
;         for (int kb = 0; kb < 8; ++kb) S[kb] = (f32x4){0.f, 0.f, 0.f, 0.f};
;     }
;     float* Ob = Og + (size_t)t0 * DA + h * 128;
;     ...
;     HgPre R0, R1, R2, R3, R4, R5;
;     R0.l1 = R0.v = (v4u){0u, 0u, 0u, 0u}; R1.l1 = R1.v = (v4u){0u, 0u, 0u, 0u}; R2.l1 = R2.v = (v4u){0u, 0u, 0u, 0u}; R3.l1 = R3.v = (v4u){0u, 0u, 0u, 0u}; R4.l1 = R4.v = (v4u){0u, 0u, 0u, 0u}; R5.l1 = R5.v = (v4u){0u, 0u, 0u, 0u};
;     HG_LOAD(R0, 0); HG_LOAD(R1, 1); HG_LOAD(R2, 2); HG_LOAD(R3, 3); HG_LOAD(R4, 4);
;     HG_STORE(R0, 0); LDSBAR();
;     for (int n = 0; n < nch; n += 6) {
;         HG_LOAD(R5, n + 5); if (active) hg_chunk(ring, S, Ob + (size_t)(n + 0) * 32 * DA, nvalid, vs, lane); if (n + 1 < nch) HG_STORE(R1, 1); LDSBAR(); if (n + 1 >= nch) break;
.Lsmpa_p4_done:
	s_add_u32 s6, s10, s36
	s_addc_u32 s7, s11, 0
	v_lshl_add_u64 v[140:141], s[6:7], 0, v[2:3]
	s_lshl_b32 s38, s50, 10
	s_add_i32 s39, s38, 0x4000
	s_add_i32 s40, s38, 0x2000
	s_mov_b32 m0, s38
	s_nop 0
	global_load_lds_dwordx4 v[210:211], off
	s_mov_b32 m0, s39
	s_nop 0
	global_load_lds_dwordx4 v[212:213], off
	s_mov_b32 m0, s40
	s_nop 0
	global_load_lds_dwordx4 v[214:215], off
	s_mov_b32 m0, s37
	s_nop 0
	global_load_lds_dwordx4 v[140:141], off
	v_lshl_add_u64 v[210:211], v[210:211], 0, s[34:35]
	v_lshl_add_u64 v[212:213], v[212:213], 0, s[34:35]
	v_lshl_add_u64 v[214:215], v[214:215], 0, s[34:35]
	v_lshl_add_u64 v[140:141], v[140:141], 0, s[34:35]
	s_add_i32 m0, s38, 0x6c00
	s_nop 0
	global_load_lds_dwordx4 v[210:211], off
	s_add_i32 m0, s39, 0x6c00
	s_nop 0
	global_load_lds_dwordx4 v[212:213], off
	s_add_i32 m0, s40, 0x6c00
	s_nop 0
	global_load_lds_dwordx4 v[214:215], off
	s_add_i32 m0, s37, 0x6c00
	s_nop 0
	global_load_lds_dwordx4 v[140:141], off
	global_load_dwordx4 v[4:7], v200, s[8:9]
	global_load_dwordx4 v[8:11], v201, s[8:9]
	global_load_dwordx4 v[12:15], v202, s[8:9]
	global_load_dwordx4 v[16:19], v203, s[8:9]
	global_load_dwordx4 v[20:23], v204, s[8:9]
	global_load_dwordx4 v[24:27], v205, s[8:9]
	global_load_dwordx4 v[28:31], v206, s[8:9]
	global_load_dwordx4 v[32:35], v207, s[8:9]
	s_add_u32 s8, s8, s34
	s_addc_u32 s9, s9, 0
	global_load_dwordx4 v[36:39], v200, s[8:9]
	global_load_dwordx4 v[40:43], v201, s[8:9]
	global_load_dwordx4 v[44:47], v202, s[8:9]
	global_load_dwordx4 v[48:51], v203, s[8:9]
	global_load_dwordx4 v[52:55], v204, s[8:9]
	global_load_dwordx4 v[56:59], v205, s[8:9]
	global_load_dwordx4 v[60:63], v206, s[8:9]
	global_load_dwordx4 v[64:67], v207, s[8:9]
	s_add_u32 s8, s8, s34
	s_addc_u32 s9, s9, 0
	s_waitcnt vmcnt(8)
	s_barrier
	v_cndmask_b32_e64 v145, v4, v5, s[42:43]
	v_cndmask_b32_e64 v147, v6, v7, s[42:43]
	s_nop 1
	v_mov_b32_dpp v146, v145 quad_perm:[1,0,3,2] row_mask:0xf bank_mask:0xf
	v_mov_b32_dpp v156, v147 quad_perm:[1,0,3,2] row_mask:0xf bank_mask:0xf
	v_cndmask_b32_e64 v5, v5, v146, s[42:43]
	v_cndmask_b32_e64 v4, v146, v4, s[42:43]
	v_cndmask_b32_e64 v7, v7, v156, s[42:43]
	v_cndmask_b32_e64 v6, v156, v6, s[42:43]
	v_cndmask_b32_e64 v145, v4, v6, s[44:45]
	v_cndmask_b32_e64 v147, v5, v7, s[44:45]
	s_nop 1
	v_mov_b32_dpp v146, v145 quad_perm:[2,3,0,1] row_mask:0xf bank_mask:0xf
	v_mov_b32_dpp v156, v147 quad_perm:[2,3,0,1] row_mask:0xf bank_mask:0xf
	v_cndmask_b32_e64 v6, v6, v146, s[44:45]
	v_cndmask_b32_e64 v4, v146, v4, s[44:45]
	v_cndmask_b32_e64 v7, v7, v156, s[44:45]
	v_cndmask_b32_e64 v5, v156, v5, s[44:45]
	v_cndmask_b32_e64 v145, v8, v9, s[42:43]
	v_cndmask_b32_e64 v147, v10, v11, s[42:43]
	s_nop 1
	v_mov_b32_dpp v146, v145 quad_perm:[1,0,3,2] row_mask:0xf bank_mask:0xf
	v_mov_b32_dpp v156, v147 quad_perm:[1,0,3,2] row_mask:0xf bank_mask:0xf
	v_cndmask_b32_e64 v9, v9, v146, s[42:43]
	v_cndmask_b32_e64 v8, v146, v8, s[42:43]
	v_cndmask_b32_e64 v11, v11, v156, s[42:43]
	v_cndmask_b32_e64 v10, v156, v10, s[42:43]
	v_cndmask_b32_e64 v145, v8, v10, s[44:45]
	v_cndmask_b32_e64 v147, v9, v11, s[44:45]
	s_nop 1
	v_mov_b32_dpp v146, v145 quad_perm:[2,3,0,1] row_mask:0xf bank_mask:0xf
	v_mov_b32_dpp v156, v147 quad_perm:[2,3,0,1] row_mask:0xf bank_mask:0xf
	v_cndmask_b32_e64 v10, v10, v146, s[44:45]
	v_cndmask_b32_e64 v8, v146, v8, s[44:45]
	v_cndmask_b32_e64 v11, v11, v156, s[44:45]
	v_cndmask_b32_e64 v9, v156, v9, s[44:45]
	v_cndmask_b32_e64 v145, v12, v13, s[42:43]
	v_cndmask_b32_e64 v147, v14, v15, s[42:43]
	s_nop 1
	v_mov_b32_dpp v146, v145 quad_perm:[1,0,3,2] row_mask:0xf bank_mask:0xf
	v_mov_b32_dpp v156, v147 quad_perm:[1,0,3,2] row_mask:0xf bank_mask:0xf
	v_cndmask_b32_e64 v13, v13, v146, s[42:43]
	v_cndmask_b32_e64 v12, v146, v12, s[42:43]
	v_cndmask_b32_e64 v15, v15, v156, s[42:43]
	v_cndmask_b32_e64 v14, v156, v14, s[42:43]
	v_cndmask_b32_e64 v145, v12, v14, s[44:45]
	v_cndmask_b32_e64 v147, v13, v15, s[44:45]
	s_nop 1
	v_mov_b32_dpp v146, v145 quad_perm:[2,3,0,1] row_mask:0xf bank_mask:0xf
	v_mov_b32_dpp v156, v147 quad_perm:[2,3,0,1] row_mask:0xf bank_mask:0xf
	v_cndmask_b32_e64 v14, v14, v146, s[44:45]
	v_cndmask_b32_e64 v12, v146, v12, s[44:45]
	v_cndmask_b32_e64 v15, v15, v156, s[44:45]
	v_cndmask_b32_e64 v13, v156, v13, s[44:45]
	v_cndmask_b32_e64 v145, v16, v17, s[42:43]
	v_cndmask_b32_e64 v147, v18, v19, s[42:43]
	s_nop 1
	v_mov_b32_dpp v146, v145 quad_perm:[1,0,3,2] row_mask:0xf bank_mask:0xf
	v_mov_b32_dpp v156, v147 quad_perm:[1,0,3,2] row_mask:0xf bank_mask:0xf
	v_cndmask_b32_e64 v17, v17, v146, s[42:43]
	v_cndmask_b32_e64 v16, v146, v16, s[42:43]
	v_cndmask_b32_e64 v19, v19, v156, s[42:43]
	v_cndmask_b32_e64 v18, v156, v18, s[42:43]
	v_cndmask_b32_e64 v145, v16, v18, s[44:45]
	v_cndmask_b32_e64 v147, v17, v19, s[44:45]
	s_nop 1
	v_mov_b32_dpp v146, v145 quad_perm:[2,3,0,1] row_mask:0xf bank_mask:0xf
	v_mov_b32_dpp v156, v147 quad_perm:[2,3,0,1] row_mask:0xf bank_mask:0xf
	v_cndmask_b32_e64 v18, v18, v146, s[44:45]
	v_cndmask_b32_e64 v16, v146, v16, s[44:45]
	v_cndmask_b32_e64 v19, v19, v156, s[44:45]
	v_cndmask_b32_e64 v17, v156, v17, s[44:45]
	v_cndmask_b32_e64 v145, v20, v21, s[42:43]
	v_cndmask_b32_e64 v147, v22, v23, s[42:43]
	s_nop 1
	v_mov_b32_dpp v146, v145 quad_perm:[1,0,3,2] row_mask:0xf bank_mask:0xf
	v_mov_b32_dpp v156, v147 quad_perm:[1,0,3,2] row_mask:0xf bank_mask:0xf
	v_cndmask_b32_e64 v21, v21, v146, s[42:43]
	v_cndmask_b32_e64 v20, v146, v20, s[42:43]
	v_cndmask_b32_e64 v23, v23, v156, s[42:43]
	v_cndmask_b32_e64 v22, v156, v22, s[42:43]
	v_cndmask_b32_e64 v145, v20, v22, s[44:45]
	v_cndmask_b32_e64 v147, v21, v23, s[44:45]
	s_nop 1
; #define LAS __attribute__((address_space(3)))
; __device__ __forceinline__ unsigned pk2(float lo, float hi) { const f32x2_t_ v = {lo, hi}; return __builtin_bit_cast(unsigned, __builtin_convertvector(v, bf16x2_t_)); }
; __device__ __forceinline__ void hg_chunk(const LAS unsigned char* sl, f32x4 (&S)[8], float* Orow, int nvalid, int vs, int lane) {
;     const int r = lane & 15, q = lane >> 4;
;     const bf16x8 vfr = *(const LAS bf16x8*)(sl + 16384 + ((vs * 64 + lane) << 4));
;     f32x4 o0 = {0.f, 0.f, 0.f, 0.f}, o1 = {0.f, 0.f, 0.f, 0.f};
;     { const bf16x8 s0 = *(const LAS bf16x8*)(sl + 24576 + (lane << 4)), s1 = *(const LAS bf16x8*)(sl + 24576 + ((64 + lane) << 4));
;       o0 = __builtin_amdgcn_mfma_f32_16x16x32_bf16(s0, vfr, o0, 0, 0, 0); o1 = __builtin_amdgcn_mfma_f32_16x16x32_bf16(s1, vfr, o1, 0, 0, 0); }
; #pragma unroll
;     for (int m = 0; m < 4; ++m) {
;         v4u sw; sw.x = pk2(S[2 * m][0], S[2 * m][1]); sw.y = pk2(S[2 * m][2], S[2 * m][3]); sw.z = pk2(S[2 * m + 1][0], S[2 * m + 1][1]); sw.w = pk2(S[2 * m + 1][2], S[2 * m + 1][3]);
;         const bf16x8 sb = __builtin_bit_cast(bf16x8, sw);
;         const bf16x8 a0 = *(const LAS bf16x8*)(sl + ((m * 64 + lane) << 4)), a1 = *(const LAS bf16x8*)(sl + (((4 + m) * 64 + lane) << 4));
;         o0 = __builtin_amdgcn_mfma_f32_16x16x32_bf16(a0, sb, o0, 0, 0, 0); o1 = __builtin_amdgcn_mfma_f32_16x16x32_bf16(a1, sb, o1, 0, 0, 0);
;     }
; #pragma unroll
;     for (int i = 0; i < 4; ++i) { const int c0 = 4 * q + i;
;         if (c0 < nvalid) Orow[(size_t)c0 * DA + 16 * vs + r] = o0[i];
;         if (c0 + 16 < nvalid) Orow[(size_t)(c0 + 16) * DA + 16 * vs + r] = o1[i]; }
; #pragma unroll
;     for (int kb = 0; kb < 8; ++kb) { const f32x4 d = *(const LAS f32x4*)(sl + 26624 + ((16 * kb + 4 * q) << 2));
;         const bf16x8 ke = *(const LAS bf16x8*)(sl + 8192 + ((kb * 64 + lane) << 4));
;         S[kb] = __builtin_amdgcn_mfma_f32_16x16x32_bf16(ke, vfr, S[kb] * d, 0, 0, 0); }
	v_mov_b32_dpp v146, v145 quad_perm:[2,3,0,1] row_mask:0xf bank_mask:0xf
	v_mov_b32_dpp v156, v147 quad_perm:[2,3,0,1] row_mask:0xf bank_mask:0xf
	v_cndmask_b32_e64 v22, v22, v146, s[44:45]
	v_cndmask_b32_e64 v20, v146, v20, s[44:45]
	v_cndmask_b32_e64 v23, v23, v156, s[44:45]
	v_cndmask_b32_e64 v21, v156, v21, s[44:45]
	v_cndmask_b32_e64 v145, v24, v25, s[42:43]
	v_cndmask_b32_e64 v147, v26, v27, s[42:43]
	s_nop 1
	v_mov_b32_dpp v146, v145 quad_perm:[1,0,3,2] row_mask:0xf bank_mask:0xf
	v_mov_b32_dpp v156, v147 quad_perm:[1,0,3,2] row_mask:0xf bank_mask:0xf
	v_cndmask_b32_e64 v25, v25, v146, s[42:43]
	v_cndmask_b32_e64 v24, v146, v24, s[42:43]
	v_cndmask_b32_e64 v27, v27, v156, s[42:43]
	v_cndmask_b32_e64 v26, v156, v26, s[42:43]
	v_cndmask_b32_e64 v145, v24, v26, s[44:45]
	v_cndmask_b32_e64 v147, v25, v27, s[44:45]
	s_nop 1
	v_mov_b32_dpp v146, v145 quad_perm:[2,3,0,1] row_mask:0xf bank_mask:0xf
	v_mov_b32_dpp v156, v147 quad_perm:[2,3,0,1] row_mask:0xf bank_mask:0xf
	v_cndmask_b32_e64 v26, v26, v146, s[44:45]
	v_cndmask_b32_e64 v24, v146, v24, s[44:45]
	v_cndmask_b32_e64 v27, v27, v156, s[44:45]
	v_cndmask_b32_e64 v25, v156, v25, s[44:45]
	v_cndmask_b32_e64 v145, v28, v29, s[42:43]
	v_cndmask_b32_e64 v147, v30, v31, s[42:43]
	s_nop 1
	v_mov_b32_dpp v146, v145 quad_perm:[1,0,3,2] row_mask:0xf bank_mask:0xf
	v_mov_b32_dpp v156, v147 quad_perm:[1,0,3,2] row_mask:0xf bank_mask:0xf
	v_cndmask_b32_e64 v29, v29, v146, s[42:43]
	v_cndmask_b32_e64 v28, v146, v28, s[42:43]
	v_cndmask_b32_e64 v31, v31, v156, s[42:43]
	v_cndmask_b32_e64 v30, v156, v30, s[42:43]
	v_cndmask_b32_e64 v145, v28, v30, s[44:45]
	v_cndmask_b32_e64 v147, v29, v31, s[44:45]
	s_nop 1
	v_mov_b32_dpp v146, v145 quad_perm:[2,3,0,1] row_mask:0xf bank_mask:0xf
	v_mov_b32_dpp v156, v147 quad_perm:[2,3,0,1] row_mask:0xf bank_mask:0xf
	v_cndmask_b32_e64 v30, v30, v146, s[44:45]
	v_cndmask_b32_e64 v28, v146, v28, s[44:45]
	v_cndmask_b32_e64 v31, v31, v156, s[44:45]
	v_cndmask_b32_e64 v29, v156, v29, s[44:45]
	v_cndmask_b32_e64 v145, v32, v33, s[42:43]
	v_cndmask_b32_e64 v147, v34, v35, s[42:43]
	s_nop 1
	v_mov_b32_dpp v146, v145 quad_perm:[1,0,3,2] row_mask:0xf bank_mask:0xf
	v_mov_b32_dpp v156, v147 quad_perm:[1,0,3,2] row_mask:0xf bank_mask:0xf
	v_cndmask_b32_e64 v33, v33, v146, s[42:43]
	v_cndmask_b32_e64 v32, v146, v32, s[42:43]
	v_cndmask_b32_e64 v35, v35, v156, s[42:43]
	v_cndmask_b32_e64 v34, v156, v34, s[42:43]
	v_cndmask_b32_e64 v145, v32, v34, s[44:45]
	v_cndmask_b32_e64 v147, v33, v35, s[44:45]
	s_nop 1
	v_mov_b32_dpp v146, v145 quad_perm:[2,3,0,1] row_mask:0xf bank_mask:0xf
	v_mov_b32_dpp v156, v147 quad_perm:[2,3,0,1] row_mask:0xf bank_mask:0xf
	v_cndmask_b32_e64 v34, v34, v146, s[44:45]
	v_cndmask_b32_e64 v32, v146, v32, s[44:45]
	v_cndmask_b32_e64 v35, v35, v156, s[44:45]
	v_cndmask_b32_e64 v33, v156, v33, s[44:45]
	v_mov_b32_e32 v1, v142
	v_mov_b32_e32 v2, v143
	v_mov_b32_e32 v3, v144
	ds_read_b128 v[164:167], v3 offset:26624
	ds_read_b128 v[168:171], v3 offset:26688
	ds_read_b128 v[172:175], v3 offset:26752
	ds_read_b128 v[176:179], v3 offset:26816
	ds_read_b128 v[180:183], v3 offset:26880
	ds_read_b128 v[184:187], v3 offset:26944
	ds_read_b128 v[148:151], v3 offset:27008
	ds_read_b128 v[152:155], v3 offset:27072
	ds_read_b128 v[84:87], v2 offset:16384
	ds_read_b128 v[88:91], v1 offset:24576
	ds_read_b128 v[92:95], v1 offset:0
	ds_read_b128 v[96:99], v1 offset:1024
	ds_read_b128 v[100:103], v1 offset:2048
	ds_read_b128 v[104:107], v1 offset:3072
	v_cvt_pk_bf16_f32 v68, v4, v5
	v_cvt_pk_bf16_f32 v69, v6, v7
	v_cvt_pk_bf16_f32 v70, v8, v9
	v_cvt_pk_bf16_f32 v71, v10, v11
	v_cvt_pk_bf16_f32 v72, v12, v13
	v_cvt_pk_bf16_f32 v73, v14, v15
	v_cvt_pk_bf16_f32 v74, v16, v17
	v_cvt_pk_bf16_f32 v75, v18, v19
	v_cvt_pk_bf16_f32 v76, v20, v21
	v_cvt_pk_bf16_f32 v77, v22, v23
	v_cvt_pk_bf16_f32 v78, v24, v25
	v_cvt_pk_bf16_f32 v79, v26, v27
	v_cvt_pk_bf16_f32 v80, v28, v29
	v_cvt_pk_bf16_f32 v81, v30, v31
	v_cvt_pk_bf16_f32 v82, v32, v33
	v_cvt_pk_bf16_f32 v83, v34, v35
	s_waitcnt lgkmcnt(6)
	v_pk_mul_f32 v[4:5], v[4:5], v[164:165]
	v_pk_mul_f32 v[6:7], v[6:7], v[166:167]
	v_pk_mul_f32 v[8:9], v[8:9], v[168:169]
	v_pk_mul_f32 v[10:11], v[10:11], v[170:171]
	v_pk_mul_f32 v[12:13], v[12:13], v[172:173]
	v_pk_mul_f32 v[14:15], v[14:15], v[174:175]
	v_pk_mul_f32 v[16:17], v[16:17], v[176:177]
	v_pk_mul_f32 v[18:19], v[18:19], v[178:179]
	v_pk_mul_f32 v[20:21], v[20:21], v[180:181]
	v_pk_mul_f32 v[22:23], v[22:23], v[182:183]
	v_pk_mul_f32 v[24:25], v[24:25], v[184:185]
	v_pk_mul_f32 v[26:27], v[26:27], v[186:187]
	v_pk_mul_f32 v[28:29], v[28:29], v[148:149]
	v_pk_mul_f32 v[30:31], v[30:31], v[150:151]
	v_pk_mul_f32 v[32:33], v[32:33], v[152:153]
	v_pk_mul_f32 v[34:35], v[34:35], v[154:155]
	ds_read_b128 v[108:111], v1 offset:8192
	ds_read_b128 v[112:115], v1 offset:9216
	ds_read_b128 v[116:119], v1 offset:10240
	ds_read_b128 v[120:123], v1 offset:11264
	ds_read_b128 v[124:127], v1 offset:12288
	ds_read_b128 v[128:131], v1 offset:13312
	ds_read_b128 v[132:135], v1 offset:14336
	ds_read_b128 v[136:139], v1 offset:15360
	s_waitcnt lgkmcnt(12)
	v_mfma_f32_16x16x32_bf16 v[196:199], v[88:91], v[84:87], 0
	s_waitcnt lgkmcnt(11)
	v_mfma_f32_16x16x32_bf16 v[196:199], v[92:95], v[68:71], v[196:199]
	s_waitcnt lgkmcnt(10)
	v_mfma_f32_16x16x32_bf16 v[196:199], v[96:99], v[72:75], v[196:199]
	s_waitcnt lgkmcnt(9)
	v_mfma_f32_16x16x32_bf16 v[196:199], v[100:103], v[76:79], v[196:199]
	s_waitcnt lgkmcnt(8)
	v_mfma_f32_16x16x32_bf16 v[196:199], v[104:107], v[80:83], v[196:199]
	s_waitcnt lgkmcnt(7)
	v_mfma_f32_16x16x32_bf16 v[4:7], v[108:111], v[84:87], v[4:7]
	s_waitcnt lgkmcnt(6)
; #define LAS __attribute__((address_space(3)))
; __device__ __forceinline__ void hg_chunk(const LAS unsigned char* sl, f32x4 (&S)[8], float* Orow, int nvalid, int vs, int lane) {
;     ...
;         o0 = __builtin_amdgcn_mfma_f32_16x16x32_bf16(a0, sb, o0, 0, 0, 0); o1 = __builtin_amdgcn_mfma_f32_16x16x32_bf16(a1, sb, o1, 0, 0, 0);
;     }
; #pragma unroll
;     for (int i = 0; i < 4; ++i) { const int c0 = 4 * q + i;
;         if (c0 < nvalid) Orow[(size_t)c0 * DA + 16 * vs + r] = o0[i];
;         if (c0 + 16 < nvalid) Orow[(size_t)(c0 + 16) * DA + 16 * vs + r] = o1[i]; }
; #pragma unroll
;     for (int kb = 0; kb < 8; ++kb) { const f32x4 d = *(const LAS f32x4*)(sl + 26624 + ((16 * kb + 4 * q) << 2));
;         const bf16x8 ke = *(const LAS bf16x8*)(sl + 8192 + ((kb * 64 + lane) << 4));
;         S[kb] = __builtin_amdgcn_mfma_f32_16x16x32_bf16(ke, vfr, S[kb] * d, 0, 0, 0); }
; __device__ __forceinline__ void hg_seq(const Frame& F, unsigned char* ws, const float* s0, float* sout, float* Og, int seq, bool sample, int vs_base, int nvs) {
;     ...
;     if (active) {
; #pragma unroll
;     for (int kb = 0; kb < 8; ++kb)
; #pragma unroll
;         for (int i = 0; i < 4; ++i) sout[((size_t)seq * 128 + 16 * kb + 4 * q + i) * 128 + 16 * vs + r] = S[kb][i];
;     }
	v_mfma_f32_16x16x32_bf16 v[8:11], v[112:115], v[84:87], v[8:11]
	s_waitcnt lgkmcnt(5)
	v_mfma_f32_16x16x32_bf16 v[12:15], v[116:119], v[84:87], v[12:15]
	s_waitcnt lgkmcnt(4)
	v_mfma_f32_16x16x32_bf16 v[16:19], v[120:123], v[84:87], v[16:19]
	s_waitcnt lgkmcnt(3)
	v_mfma_f32_16x16x32_bf16 v[20:23], v[124:127], v[84:87], v[20:23]
	s_waitcnt lgkmcnt(2)
	v_mfma_f32_16x16x32_bf16 v[24:27], v[128:131], v[84:87], v[24:27]
	s_waitcnt lgkmcnt(1)
	v_mfma_f32_16x16x32_bf16 v[28:31], v[132:135], v[84:87], v[28:31]
	s_waitcnt lgkmcnt(0)
	v_mfma_f32_16x16x32_bf16 v[32:35], v[136:139], v[84:87], v[32:35]
	s_mov_b32 exec_hi, 0
	global_store_dword v208, v196, s[12:13]
	global_store_dword v208, v197, s[12:13] offset:2048
	global_store_dword v209, v198, s[12:13]
	global_store_dword v209, v199, s[12:13] offset:2048
	s_mov_b64 exec, -1
	s_add_u32 s12, s12, 0x80000
	s_addc_u32 s13, s13, 0
	s_nop 7
	v_cndmask_b32_e64 v145, v4, v5, s[42:43]
	v_cndmask_b32_e64 v147, v6, v7, s[42:43]
	s_nop 1
	v_mov_b32_dpp v146, v145 quad_perm:[1,0,3,2] row_mask:0xf bank_mask:0xf
	v_mov_b32_dpp v156, v147 quad_perm:[1,0,3,2] row_mask:0xf bank_mask:0xf
	v_cndmask_b32_e64 v5, v5, v146, s[42:43]
	v_cndmask_b32_e64 v4, v146, v4, s[42:43]
	v_cndmask_b32_e64 v7, v7, v156, s[42:43]
	v_cndmask_b32_e64 v6, v156, v6, s[42:43]
	v_cndmask_b32_e64 v145, v4, v6, s[44:45]
	v_cndmask_b32_e64 v147, v5, v7, s[44:45]
	s_nop 1
	v_mov_b32_dpp v146, v145 quad_perm:[2,3,0,1] row_mask:0xf bank_mask:0xf
	v_mov_b32_dpp v156, v147 quad_perm:[2,3,0,1] row_mask:0xf bank_mask:0xf
	v_cndmask_b32_e64 v6, v6, v146, s[44:45]
	v_cndmask_b32_e64 v4, v146, v4, s[44:45]
	v_cndmask_b32_e64 v7, v7, v156, s[44:45]
	v_cndmask_b32_e64 v5, v156, v5, s[44:45]
	v_cndmask_b32_e64 v145, v8, v9, s[42:43]
	v_cndmask_b32_e64 v147, v10, v11, s[42:43]
	s_nop 1
	v_mov_b32_dpp v146, v145 quad_perm:[1,0,3,2] row_mask:0xf bank_mask:0xf
	v_mov_b32_dpp v156, v147 quad_perm:[1,0,3,2] row_mask:0xf bank_mask:0xf
	v_cndmask_b32_e64 v9, v9, v146, s[42:43]
	v_cndmask_b32_e64 v8, v146, v8, s[42:43]
	v_cndmask_b32_e64 v11, v11, v156, s[42:43]
	v_cndmask_b32_e64 v10, v156, v10, s[42:43]
	v_cndmask_b32_e64 v145, v8, v10, s[44:45]
	v_cndmask_b32_e64 v147, v9, v11, s[44:45]
	s_nop 1
	v_mov_b32_dpp v146, v145 quad_perm:[2,3,0,1] row_mask:0xf bank_mask:0xf
	v_mov_b32_dpp v156, v147 quad_perm:[2,3,0,1] row_mask:0xf bank_mask:0xf
	v_cndmask_b32_e64 v10, v10, v146, s[44:45]
	v_cndmask_b32_e64 v8, v146, v8, s[44:45]
	v_cndmask_b32_e64 v11, v11, v156, s[44:45]
	v_cndmask_b32_e64 v9, v156, v9, s[44:45]
	v_cndmask_b32_e64 v145, v12, v13, s[42:43]
	v_cndmask_b32_e64 v147, v14, v15, s[42:43]
	s_nop 1
	v_mov_b32_dpp v146, v145 quad_perm:[1,0,3,2] row_mask:0xf bank_mask:0xf
	v_mov_b32_dpp v156, v147 quad_perm:[1,0,3,2] row_mask:0xf bank_mask:0xf
	v_cndmask_b32_e64 v13, v13, v146, s[42:43]
	v_cndmask_b32_e64 v12, v146, v12, s[42:43]
	v_cndmask_b32_e64 v15, v15, v156, s[42:43]
	v_cndmask_b32_e64 v14, v156, v14, s[42:43]
	v_cndmask_b32_e64 v145, v12, v14, s[44:45]
	v_cndmask_b32_e64 v147, v13, v15, s[44:45]
	s_nop 1
	v_mov_b32_dpp v146, v145 quad_perm:[2,3,0,1] row_mask:0xf bank_mask:0xf
	v_mov_b32_dpp v156, v147 quad_perm:[2,3,0,1] row_mask:0xf bank_mask:0xf
	v_cndmask_b32_e64 v14, v14, v146, s[44:45]
	v_cndmask_b32_e64 v12, v146, v12, s[44:45]
	v_cndmask_b32_e64 v15, v15, v156, s[44:45]
	v_cndmask_b32_e64 v13, v156, v13, s[44:45]
	v_cndmask_b32_e64 v145, v16, v17, s[42:43]
	v_cndmask_b32_e64 v147, v18, v19, s[42:43]
	s_nop 1
	v_mov_b32_dpp v146, v145 quad_perm:[1,0,3,2] row_mask:0xf bank_mask:0xf
	v_mov_b32_dpp v156, v147 quad_perm:[1,0,3,2] row_mask:0xf bank_mask:0xf
	v_cndmask_b32_e64 v17, v17, v146, s[42:43]
	v_cndmask_b32_e64 v16, v146, v16, s[42:43]
	v_cndmask_b32_e64 v19, v19, v156, s[42:43]
	v_cndmask_b32_e64 v18, v156, v18, s[42:43]
	v_cndmask_b32_e64 v145, v16, v18, s[44:45]
	v_cndmask_b32_e64 v147, v17, v19, s[44:45]
	s_nop 1
	v_mov_b32_dpp v146, v145 quad_perm:[2,3,0,1] row_mask:0xf bank_mask:0xf
	v_mov_b32_dpp v156, v147 quad_perm:[2,3,0,1] row_mask:0xf bank_mask:0xf
	v_cndmask_b32_e64 v18, v18, v146, s[44:45]
	v_cndmask_b32_e64 v16, v146, v16, s[44:45]
	v_cndmask_b32_e64 v19, v19, v156, s[44:45]
	v_cndmask_b32_e64 v17, v156, v17, s[44:45]
	v_cndmask_b32_e64 v145, v20, v21, s[42:43]
	v_cndmask_b32_e64 v147, v22, v23, s[42:43]
	s_nop 1
	v_mov_b32_dpp v146, v145 quad_perm:[1,0,3,2] row_mask:0xf bank_mask:0xf
	v_mov_b32_dpp v156, v147 quad_perm:[1,0,3,2] row_mask:0xf bank_mask:0xf
	v_cndmask_b32_e64 v21, v21, v146, s[42:43]
	v_cndmask_b32_e64 v20, v146, v20, s[42:43]
	v_cndmask_b32_e64 v23, v23, v156, s[42:43]
	v_cndmask_b32_e64 v22, v156, v22, s[42:43]
	v_cndmask_b32_e64 v145, v20, v22, s[44:45]
	v_cndmask_b32_e64 v147, v21, v23, s[44:45]
	s_nop 1
	v_mov_b32_dpp v146, v145 quad_perm:[2,3,0,1] row_mask:0xf bank_mask:0xf
	v_mov_b32_dpp v156, v147 quad_perm:[2,3,0,1] row_mask:0xf bank_mask:0xf
	v_cndmask_b32_e64 v22, v22, v146, s[44:45]
	v_cndmask_b32_e64 v20, v146, v20, s[44:45]
	v_cndmask_b32_e64 v23, v23, v156, s[44:45]
	v_cndmask_b32_e64 v21, v156, v21, s[44:45]
	v_cndmask_b32_e64 v145, v24, v25, s[42:43]
	v_cndmask_b32_e64 v147, v26, v27, s[42:43]
	s_nop 1
	v_mov_b32_dpp v146, v145 quad_perm:[1,0,3,2] row_mask:0xf bank_mask:0xf
	v_mov_b32_dpp v156, v147 quad_perm:[1,0,3,2] row_mask:0xf bank_mask:0xf
	v_cndmask_b32_e64 v25, v25, v146, s[42:43]
	v_cndmask_b32_e64 v24, v146, v24, s[42:43]
	v_cndmask_b32_e64 v27, v27, v156, s[42:43]
	v_cndmask_b32_e64 v26, v156, v26, s[42:43]
	v_cndmask_b32_e64 v145, v24, v26, s[44:45]
	v_cndmask_b32_e64 v147, v25, v27, s[44:45]
	s_nop 1
	v_mov_b32_dpp v146, v145 quad_perm:[2,3,0,1] row_mask:0xf bank_mask:0xf
; __device__ __forceinline__ void hg_seq(const Frame& F, unsigned char* ws, const float* s0, float* sout, float* Og, int seq, bool sample, int vs_base, int nvs) {
;     ...
;     if (sample && active) {
; #pragma unroll
;         for (int kb = 0; kb < 8; ++kb)
; #pragma unroll
;             for (int i = 0; i < 4; ++i) S[kb][i] = s0[((size_t)seq * 128 + 16 * kb + 4 * q + i) * 128 + 16 * vs + r];
;     } else {
;     ...
;     if (active) {
; #pragma unroll
;     for (int kb = 0; kb < 8; ++kb)
; #pragma unroll
;         for (int i = 0; i < 4; ++i) sout[((size_t)seq * 128 + 16 * kb + 4 * q + i) * 128 + 16 * vs + r] = S[kb][i];
;     }
	v_mov_b32_dpp v156, v147 quad_perm:[2,3,0,1] row_mask:0xf bank_mask:0xf
	v_cndmask_b32_e64 v26, v26, v146, s[44:45]
	v_cndmask_b32_e64 v24, v146, v24, s[44:45]
	v_cndmask_b32_e64 v27, v27, v156, s[44:45]
	v_cndmask_b32_e64 v25, v156, v25, s[44:45]
	v_cndmask_b32_e64 v145, v28, v29, s[42:43]
	v_cndmask_b32_e64 v147, v30, v31, s[42:43]
	s_nop 1
	v_mov_b32_dpp v146, v145 quad_perm:[1,0,3,2] row_mask:0xf bank_mask:0xf
	v_mov_b32_dpp v156, v147 quad_perm:[1,0,3,2] row_mask:0xf bank_mask:0xf
	v_cndmask_b32_e64 v29, v29, v146, s[42:43]
	v_cndmask_b32_e64 v28, v146, v28, s[42:43]
	v_cndmask_b32_e64 v31, v31, v156, s[42:43]
	v_cndmask_b32_e64 v30, v156, v30, s[42:43]
	v_cndmask_b32_e64 v145, v28, v30, s[44:45]
	v_cndmask_b32_e64 v147, v29, v31, s[44:45]
	s_nop 1
	v_mov_b32_dpp v146, v145 quad_perm:[2,3,0,1] row_mask:0xf bank_mask:0xf
	v_mov_b32_dpp v156, v147 quad_perm:[2,3,0,1] row_mask:0xf bank_mask:0xf
	v_cndmask_b32_e64 v30, v30, v146, s[44:45]
	v_cndmask_b32_e64 v28, v146, v28, s[44:45]
	v_cndmask_b32_e64 v31, v31, v156, s[44:45]
	v_cndmask_b32_e64 v29, v156, v29, s[44:45]
	v_cndmask_b32_e64 v145, v32, v33, s[42:43]
	v_cndmask_b32_e64 v147, v34, v35, s[42:43]
	s_nop 1
	v_mov_b32_dpp v146, v145 quad_perm:[1,0,3,2] row_mask:0xf bank_mask:0xf
	v_mov_b32_dpp v156, v147 quad_perm:[1,0,3,2] row_mask:0xf bank_mask:0xf
	v_cndmask_b32_e64 v33, v33, v146, s[42:43]
	v_cndmask_b32_e64 v32, v146, v32, s[42:43]
	v_cndmask_b32_e64 v35, v35, v156, s[42:43]
	v_cndmask_b32_e64 v34, v156, v34, s[42:43]
	v_cndmask_b32_e64 v145, v32, v34, s[44:45]
	v_cndmask_b32_e64 v147, v33, v35, s[44:45]
	s_nop 1
	v_mov_b32_dpp v146, v145 quad_perm:[2,3,0,1] row_mask:0xf bank_mask:0xf
	v_mov_b32_dpp v156, v147 quad_perm:[2,3,0,1] row_mask:0xf bank_mask:0xf
	v_cndmask_b32_e64 v34, v34, v146, s[44:45]
	v_cndmask_b32_e64 v32, v146, v32, s[44:45]
	v_cndmask_b32_e64 v35, v35, v156, s[44:45]
	v_cndmask_b32_e64 v33, v156, v33, s[44:45]
	global_store_dwordx4 v200, v[4:7], s[10:11]
	global_store_dwordx4 v201, v[8:11], s[10:11]
	global_store_dwordx4 v202, v[12:15], s[10:11]
	global_store_dwordx4 v203, v[16:19], s[10:11]
	global_store_dwordx4 v204, v[20:23], s[10:11]
	global_store_dwordx4 v205, v[24:27], s[10:11]
	global_store_dwordx4 v206, v[28:31], s[10:11]
	global_store_dwordx4 v207, v[32:35], s[10:11]
	s_add_u32 s10, s10, s34
	s_addc_u32 s11, s11, 0
	s_waitcnt vmcnt(12)
	v_cndmask_b32_e64 v145, v36, v37, s[42:43]
	v_cndmask_b32_e64 v147, v38, v39, s[42:43]
	s_nop 1
	v_mov_b32_dpp v146, v145 quad_perm:[1,0,3,2] row_mask:0xf bank_mask:0xf
	v_mov_b32_dpp v156, v147 quad_perm:[1,0,3,2] row_mask:0xf bank_mask:0xf
	v_cndmask_b32_e64 v37, v37, v146, s[42:43]
	v_cndmask_b32_e64 v36, v146, v36, s[42:43]
	v_cndmask_b32_e64 v39, v39, v156, s[42:43]
	v_cndmask_b32_e64 v38, v156, v38, s[42:43]
	v_cndmask_b32_e64 v145, v36, v38, s[44:45]
	v_cndmask_b32_e64 v147, v37, v39, s[44:45]
	s_nop 1
	v_mov_b32_dpp v146, v145 quad_perm:[2,3,0,1] row_mask:0xf bank_mask:0xf
	v_mov_b32_dpp v156, v147 quad_perm:[2,3,0,1] row_mask:0xf bank_mask:0xf
	v_cndmask_b32_e64 v38, v38, v146, s[44:45]
	v_cndmask_b32_e64 v36, v146, v36, s[44:45]
	v_cndmask_b32_e64 v39, v39, v156, s[44:45]
	v_cndmask_b32_e64 v37, v156, v37, s[44:45]
	v_cndmask_b32_e64 v145, v40, v41, s[42:43]
	v_cndmask_b32_e64 v147, v42, v43, s[42:43]
	s_nop 1
	v_mov_b32_dpp v146, v145 quad_perm:[1,0,3,2] row_mask:0xf bank_mask:0xf
	v_mov_b32_dpp v156, v147 quad_perm:[1,0,3,2] row_mask:0xf bank_mask:0xf
	v_cndmask_b32_e64 v41, v41, v146, s[42:43]
	v_cndmask_b32_e64 v40, v146, v40, s[42:43]
	v_cndmask_b32_e64 v43, v43, v156, s[42:43]
	v_cndmask_b32_e64 v42, v156, v42, s[42:43]
	v_cndmask_b32_e64 v145, v40, v42, s[44:45]
	v_cndmask_b32_e64 v147, v41, v43, s[44:45]
	s_nop 1
	v_mov_b32_dpp v146, v145 quad_perm:[2,3,0,1] row_mask:0xf bank_mask:0xf
	v_mov_b32_dpp v156, v147 quad_perm:[2,3,0,1] row_mask:0xf bank_mask:0xf
	v_cndmask_b32_e64 v42, v42, v146, s[44:45]
	v_cndmask_b32_e64 v40, v146, v40, s[44:45]
	v_cndmask_b32_e64 v43, v43, v156, s[44:45]
	v_cndmask_b32_e64 v41, v156, v41, s[44:45]
	v_cndmask_b32_e64 v145, v44, v45, s[42:43]
	v_cndmask_b32_e64 v147, v46, v47, s[42:43]
	s_nop 1
	v_mov_b32_dpp v146, v145 quad_perm:[1,0,3,2] row_mask:0xf bank_mask:0xf
	v_mov_b32_dpp v156, v147 quad_perm:[1,0,3,2] row_mask:0xf bank_mask:0xf
	v_cndmask_b32_e64 v45, v45, v146, s[42:43]
	v_cndmask_b32_e64 v44, v146, v44, s[42:43]
	v_cndmask_b32_e64 v47, v47, v156, s[42:43]
	v_cndmask_b32_e64 v46, v156, v46, s[42:43]
	v_cndmask_b32_e64 v145, v44, v46, s[44:45]
	v_cndmask_b32_e64 v147, v45, v47, s[44:45]
	s_nop 1
	v_mov_b32_dpp v146, v145 quad_perm:[2,3,0,1] row_mask:0xf bank_mask:0xf
	v_mov_b32_dpp v156, v147 quad_perm:[2,3,0,1] row_mask:0xf bank_mask:0xf
	v_cndmask_b32_e64 v46, v46, v146, s[44:45]
	v_cndmask_b32_e64 v44, v146, v44, s[44:45]
	v_cndmask_b32_e64 v47, v47, v156, s[44:45]
	v_cndmask_b32_e64 v45, v156, v45, s[44:45]
	v_cndmask_b32_e64 v145, v48, v49, s[42:43]
	v_cndmask_b32_e64 v147, v50, v51, s[42:43]
	s_nop 1
	v_mov_b32_dpp v146, v145 quad_perm:[1,0,3,2] row_mask:0xf bank_mask:0xf
	v_mov_b32_dpp v156, v147 quad_perm:[1,0,3,2] row_mask:0xf bank_mask:0xf
	v_cndmask_b32_e64 v49, v49, v146, s[42:43]
	v_cndmask_b32_e64 v48, v146, v48, s[42:43]
	v_cndmask_b32_e64 v51, v51, v156, s[42:43]
	v_cndmask_b32_e64 v50, v156, v50, s[42:43]
	v_cndmask_b32_e64 v145, v48, v50, s[44:45]
	v_cndmask_b32_e64 v147, v49, v51, s[44:45]
	s_nop 1
	v_mov_b32_dpp v146, v145 quad_perm:[2,3,0,1] row_mask:0xf bank_mask:0xf
	v_mov_b32_dpp v156, v147 quad_perm:[2,3,0,1] row_mask:0xf bank_mask:0xf
	v_cndmask_b32_e64 v50, v50, v146, s[44:45]
	v_cndmask_b32_e64 v48, v146, v48, s[44:45]
; #define LAS __attribute__((address_space(3)))
; __device__ __forceinline__ unsigned pk2(float lo, float hi) { const f32x2_t_ v = {lo, hi}; return __builtin_bit_cast(unsigned, __builtin_convertvector(v, bf16x2_t_)); }
; __device__ __forceinline__ void hg_chunk(const LAS unsigned char* sl, f32x4 (&S)[8], float* Orow, int nvalid, int vs, int lane) {
;     const int r = lane & 15, q = lane >> 4;
;     const bf16x8 vfr = *(const LAS bf16x8*)(sl + 16384 + ((vs * 64 + lane) << 4));
;     f32x4 o0 = {0.f, 0.f, 0.f, 0.f}, o1 = {0.f, 0.f, 0.f, 0.f};
;     { const bf16x8 s0 = *(const LAS bf16x8*)(sl + 24576 + (lane << 4)), s1 = *(const LAS bf16x8*)(sl + 24576 + ((64 + lane) << 4));
;       o0 = __builtin_amdgcn_mfma_f32_16x16x32_bf16(s0, vfr, o0, 0, 0, 0); o1 = __builtin_amdgcn_mfma_f32_16x16x32_bf16(s1, vfr, o1, 0, 0, 0); }
; #pragma unroll
;     for (int m = 0; m < 4; ++m) {
;         v4u sw; sw.x = pk2(S[2 * m][0], S[2 * m][1]); sw.y = pk2(S[2 * m][2], S[2 * m][3]); sw.z = pk2(S[2 * m + 1][0], S[2 * m + 1][1]); sw.w = pk2(S[2 * m + 1][2], S[2 * m + 1][3]);
;         const bf16x8 sb = __builtin_bit_cast(bf16x8, sw);
;         const bf16x8 a0 = *(const LAS bf16x8*)(sl + ((m * 64 + lane) << 4)), a1 = *(const LAS bf16x8*)(sl + (((4 + m) * 64 + lane) << 4));
; __device__ __forceinline__ void hg_seq(const Frame& F, unsigned char* ws, const float* s0, float* sout, float* Og, int seq, bool sample, int vs_base, int nvs) {
;     ...
;     if (sample && active) {
; #pragma unroll
;         for (int kb = 0; kb < 8; ++kb)
; #pragma unroll
;             for (int i = 0; i < 4; ++i) S[kb][i] = s0[((size_t)seq * 128 + 16 * kb + 4 * q + i) * 128 + 16 * vs + r];
;     } else {
	v_cndmask_b32_e64 v51, v51, v156, s[44:45]
	v_cndmask_b32_e64 v49, v156, v49, s[44:45]
	v_cndmask_b32_e64 v145, v52, v53, s[42:43]
	v_cndmask_b32_e64 v147, v54, v55, s[42:43]
	s_nop 1
	v_mov_b32_dpp v146, v145 quad_perm:[1,0,3,2] row_mask:0xf bank_mask:0xf
	v_mov_b32_dpp v156, v147 quad_perm:[1,0,3,2] row_mask:0xf bank_mask:0xf
	v_cndmask_b32_e64 v53, v53, v146, s[42:43]
	v_cndmask_b32_e64 v52, v146, v52, s[42:43]
	v_cndmask_b32_e64 v55, v55, v156, s[42:43]
	v_cndmask_b32_e64 v54, v156, v54, s[42:43]
	v_cndmask_b32_e64 v145, v52, v54, s[44:45]
	v_cndmask_b32_e64 v147, v53, v55, s[44:45]
	s_nop 1
	v_mov_b32_dpp v146, v145 quad_perm:[2,3,0,1] row_mask:0xf bank_mask:0xf
	v_mov_b32_dpp v156, v147 quad_perm:[2,3,0,1] row_mask:0xf bank_mask:0xf
	v_cndmask_b32_e64 v54, v54, v146, s[44:45]
	v_cndmask_b32_e64 v52, v146, v52, s[44:45]
	v_cndmask_b32_e64 v55, v55, v156, s[44:45]
	v_cndmask_b32_e64 v53, v156, v53, s[44:45]
	v_cndmask_b32_e64 v145, v56, v57, s[42:43]
	v_cndmask_b32_e64 v147, v58, v59, s[42:43]
	s_nop 1
	v_mov_b32_dpp v146, v145 quad_perm:[1,0,3,2] row_mask:0xf bank_mask:0xf
	v_mov_b32_dpp v156, v147 quad_perm:[1,0,3,2] row_mask:0xf bank_mask:0xf
	v_cndmask_b32_e64 v57, v57, v146, s[42:43]
	v_cndmask_b32_e64 v56, v146, v56, s[42:43]
	v_cndmask_b32_e64 v59, v59, v156, s[42:43]
	v_cndmask_b32_e64 v58, v156, v58, s[42:43]
	v_cndmask_b32_e64 v145, v56, v58, s[44:45]
	v_cndmask_b32_e64 v147, v57, v59, s[44:45]
	s_nop 1
	v_mov_b32_dpp v146, v145 quad_perm:[2,3,0,1] row_mask:0xf bank_mask:0xf
	v_mov_b32_dpp v156, v147 quad_perm:[2,3,0,1] row_mask:0xf bank_mask:0xf
	v_cndmask_b32_e64 v58, v58, v146, s[44:45]
	v_cndmask_b32_e64 v56, v146, v56, s[44:45]
	v_cndmask_b32_e64 v59, v59, v156, s[44:45]
	v_cndmask_b32_e64 v57, v156, v57, s[44:45]
	v_cndmask_b32_e64 v145, v60, v61, s[42:43]
	v_cndmask_b32_e64 v147, v62, v63, s[42:43]
	s_nop 1
	v_mov_b32_dpp v146, v145 quad_perm:[1,0,3,2] row_mask:0xf bank_mask:0xf
	v_mov_b32_dpp v156, v147 quad_perm:[1,0,3,2] row_mask:0xf bank_mask:0xf
	v_cndmask_b32_e64 v61, v61, v146, s[42:43]
	v_cndmask_b32_e64 v60, v146, v60, s[42:43]
	v_cndmask_b32_e64 v63, v63, v156, s[42:43]
	v_cndmask_b32_e64 v62, v156, v62, s[42:43]
	v_cndmask_b32_e64 v145, v60, v62, s[44:45]
	v_cndmask_b32_e64 v147, v61, v63, s[44:45]
	s_nop 1
	v_mov_b32_dpp v146, v145 quad_perm:[2,3,0,1] row_mask:0xf bank_mask:0xf
	v_mov_b32_dpp v156, v147 quad_perm:[2,3,0,1] row_mask:0xf bank_mask:0xf
	v_cndmask_b32_e64 v62, v62, v146, s[44:45]
	v_cndmask_b32_e64 v60, v146, v60, s[44:45]
	v_cndmask_b32_e64 v63, v63, v156, s[44:45]
	v_cndmask_b32_e64 v61, v156, v61, s[44:45]
	v_cndmask_b32_e64 v145, v64, v65, s[42:43]
	v_cndmask_b32_e64 v147, v66, v67, s[42:43]
	s_nop 1
	v_mov_b32_dpp v146, v145 quad_perm:[1,0,3,2] row_mask:0xf bank_mask:0xf
	v_mov_b32_dpp v156, v147 quad_perm:[1,0,3,2] row_mask:0xf bank_mask:0xf
	v_cndmask_b32_e64 v65, v65, v146, s[42:43]
	v_cndmask_b32_e64 v64, v146, v64, s[42:43]
	v_cndmask_b32_e64 v67, v67, v156, s[42:43]
	v_cndmask_b32_e64 v66, v156, v66, s[42:43]
	v_cndmask_b32_e64 v145, v64, v66, s[44:45]
	v_cndmask_b32_e64 v147, v65, v67, s[44:45]
	s_nop 1
	v_mov_b32_dpp v146, v145 quad_perm:[2,3,0,1] row_mask:0xf bank_mask:0xf
	v_mov_b32_dpp v156, v147 quad_perm:[2,3,0,1] row_mask:0xf bank_mask:0xf
	v_cndmask_b32_e64 v66, v66, v146, s[44:45]
	v_cndmask_b32_e64 v64, v146, v64, s[44:45]
	v_cndmask_b32_e64 v67, v67, v156, s[44:45]
	v_cndmask_b32_e64 v65, v156, v65, s[44:45]
	v_add_u32_e32 v1, 0x6c00, v142
	v_add_u32_e32 v2, 0x6c00, v143
	v_add_u32_e32 v3, 0x6c00, v144
	ds_read_b128 v[164:167], v3 offset:26624
	ds_read_b128 v[168:171], v3 offset:26688
	ds_read_b128 v[172:175], v3 offset:26752
	ds_read_b128 v[176:179], v3 offset:26816
	ds_read_b128 v[180:183], v3 offset:26880
	ds_read_b128 v[184:187], v3 offset:26944
	ds_read_b128 v[148:151], v3 offset:27008
	ds_read_b128 v[152:155], v3 offset:27072
	ds_read_b128 v[84:87], v2 offset:16384
	ds_read_b128 v[88:91], v1 offset:24576
	ds_read_b128 v[92:95], v1 offset:0
	ds_read_b128 v[96:99], v1 offset:1024
	ds_read_b128 v[100:103], v1 offset:2048
	ds_read_b128 v[104:107], v1 offset:3072
	v_cvt_pk_bf16_f32 v68, v36, v37
	v_cvt_pk_bf16_f32 v69, v38, v39
	v_cvt_pk_bf16_f32 v70, v40, v41
	v_cvt_pk_bf16_f32 v71, v42, v43
	v_cvt_pk_bf16_f32 v72, v44, v45
	v_cvt_pk_bf16_f32 v73, v46, v47
	v_cvt_pk_bf16_f32 v74, v48, v49
	v_cvt_pk_bf16_f32 v75, v50, v51
	v_cvt_pk_bf16_f32 v76, v52, v53
	v_cvt_pk_bf16_f32 v77, v54, v55
	v_cvt_pk_bf16_f32 v78, v56, v57
	v_cvt_pk_bf16_f32 v79, v58, v59
	v_cvt_pk_bf16_f32 v80, v60, v61
	v_cvt_pk_bf16_f32 v81, v62, v63
	v_cvt_pk_bf16_f32 v82, v64, v65
	v_cvt_pk_bf16_f32 v83, v66, v67
	s_waitcnt lgkmcnt(6)
	v_pk_mul_f32 v[36:37], v[36:37], v[164:165]
	v_pk_mul_f32 v[38:39], v[38:39], v[166:167]
	v_pk_mul_f32 v[40:41], v[40:41], v[168:169]
	v_pk_mul_f32 v[42:43], v[42:43], v[170:171]
	v_pk_mul_f32 v[44:45], v[44:45], v[172:173]
	v_pk_mul_f32 v[46:47], v[46:47], v[174:175]
	v_pk_mul_f32 v[48:49], v[48:49], v[176:177]
	v_pk_mul_f32 v[50:51], v[50:51], v[178:179]
	v_pk_mul_f32 v[52:53], v[52:53], v[180:181]
	v_pk_mul_f32 v[54:55], v[54:55], v[182:183]
	v_pk_mul_f32 v[56:57], v[56:57], v[184:185]
	v_pk_mul_f32 v[58:59], v[58:59], v[186:187]
	v_pk_mul_f32 v[60:61], v[60:61], v[148:149]
	v_pk_mul_f32 v[62:63], v[62:63], v[150:151]
	v_pk_mul_f32 v[64:65], v[64:65], v[152:153]
	v_pk_mul_f32 v[66:67], v[66:67], v[154:155]
	ds_read_b128 v[108:111], v1 offset:8192
	ds_read_b128 v[112:115], v1 offset:9216
	ds_read_b128 v[116:119], v1 offset:10240
	ds_read_b128 v[120:123], v1 offset:11264
	ds_read_b128 v[124:127], v1 offset:12288
	ds_read_b128 v[128:131], v1 offset:13312
	ds_read_b128 v[132:135], v1 offset:14336
	ds_read_b128 v[136:139], v1 offset:15360
	s_waitcnt lgkmcnt(12)
; #define LAS __attribute__((address_space(3)))
; __device__ __forceinline__ void hg_chunk(const LAS unsigned char* sl, f32x4 (&S)[8], float* Orow, int nvalid, int vs, int lane) {
;     ...
;         o0 = __builtin_amdgcn_mfma_f32_16x16x32_bf16(a0, sb, o0, 0, 0, 0); o1 = __builtin_amdgcn_mfma_f32_16x16x32_bf16(a1, sb, o1, 0, 0, 0);
;     }
; #pragma unroll
;     for (int i = 0; i < 4; ++i) { const int c0 = 4 * q + i;
;         if (c0 < nvalid) Orow[(size_t)c0 * DA + 16 * vs + r] = o0[i];
;         if (c0 + 16 < nvalid) Orow[(size_t)(c0 + 16) * DA + 16 * vs + r] = o1[i]; }
; #pragma unroll
;     for (int kb = 0; kb < 8; ++kb) { const f32x4 d = *(const LAS f32x4*)(sl + 26624 + ((16 * kb + 4 * q) << 2));
;         const bf16x8 ke = *(const LAS bf16x8*)(sl + 8192 + ((kb * 64 + lane) << 4));
;         S[kb] = __builtin_amdgcn_mfma_f32_16x16x32_bf16(ke, vfr, S[kb] * d, 0, 0, 0); }
; __device__ __forceinline__ void hg_seq(const Frame& F, unsigned char* ws, const float* s0, float* sout, float* Og, int seq, bool sample, int vs_base, int nvs) {
;     ...
;     if (active) {
; #pragma unroll
;     for (int kb = 0; kb < 8; ++kb)
; #pragma unroll
;         for (int i = 0; i < 4; ++i) sout[((size_t)seq * 128 + 16 * kb + 4 * q + i) * 128 + 16 * vs + r] = S[kb][i];
;     }
	v_mfma_f32_16x16x32_bf16 v[196:199], v[88:91], v[84:87], 0
	s_waitcnt lgkmcnt(11)
	v_mfma_f32_16x16x32_bf16 v[196:199], v[92:95], v[68:71], v[196:199]
	s_waitcnt lgkmcnt(10)
	v_mfma_f32_16x16x32_bf16 v[196:199], v[96:99], v[72:75], v[196:199]
	s_waitcnt lgkmcnt(9)
	v_mfma_f32_16x16x32_bf16 v[196:199], v[100:103], v[76:79], v[196:199]
	s_waitcnt lgkmcnt(8)
	v_mfma_f32_16x16x32_bf16 v[196:199], v[104:107], v[80:83], v[196:199]
	s_waitcnt lgkmcnt(7)
	v_mfma_f32_16x16x32_bf16 v[36:39], v[108:111], v[84:87], v[36:39]
	s_waitcnt lgkmcnt(6)
	v_mfma_f32_16x16x32_bf16 v[40:43], v[112:115], v[84:87], v[40:43]
	s_waitcnt lgkmcnt(5)
	v_mfma_f32_16x16x32_bf16 v[44:47], v[116:119], v[84:87], v[44:47]
	s_waitcnt lgkmcnt(4)
	v_mfma_f32_16x16x32_bf16 v[48:51], v[120:123], v[84:87], v[48:51]
	s_waitcnt lgkmcnt(3)
	v_mfma_f32_16x16x32_bf16 v[52:55], v[124:127], v[84:87], v[52:55]
	s_waitcnt lgkmcnt(2)
	v_mfma_f32_16x16x32_bf16 v[56:59], v[128:131], v[84:87], v[56:59]
	s_waitcnt lgkmcnt(1)
	v_mfma_f32_16x16x32_bf16 v[60:63], v[132:135], v[84:87], v[60:63]
	s_waitcnt lgkmcnt(0)
	v_mfma_f32_16x16x32_bf16 v[64:67], v[136:139], v[84:87], v[64:67]
	s_mov_b32 exec_hi, 0
	global_store_dword v208, v196, s[12:13]
	global_store_dword v208, v197, s[12:13] offset:2048
	global_store_dword v209, v198, s[12:13]
	global_store_dword v209, v199, s[12:13] offset:2048
	s_mov_b64 exec, -1
	s_add_u32 s12, s12, 0x80000
	s_addc_u32 s13, s13, 0
	s_nop 7
	v_cndmask_b32_e64 v145, v36, v37, s[42:43]
	v_cndmask_b32_e64 v147, v38, v39, s[42:43]
	s_nop 1
	v_mov_b32_dpp v146, v145 quad_perm:[1,0,3,2] row_mask:0xf bank_mask:0xf
	v_mov_b32_dpp v156, v147 quad_perm:[1,0,3,2] row_mask:0xf bank_mask:0xf
	v_cndmask_b32_e64 v37, v37, v146, s[42:43]
	v_cndmask_b32_e64 v36, v146, v36, s[42:43]
	v_cndmask_b32_e64 v39, v39, v156, s[42:43]
	v_cndmask_b32_e64 v38, v156, v38, s[42:43]
	v_cndmask_b32_e64 v145, v36, v38, s[44:45]
	v_cndmask_b32_e64 v147, v37, v39, s[44:45]
	s_nop 1
	v_mov_b32_dpp v146, v145 quad_perm:[2,3,0,1] row_mask:0xf bank_mask:0xf
	v_mov_b32_dpp v156, v147 quad_perm:[2,3,0,1] row_mask:0xf bank_mask:0xf
	v_cndmask_b32_e64 v38, v38, v146, s[44:45]
	v_cndmask_b32_e64 v36, v146, v36, s[44:45]
	v_cndmask_b32_e64 v39, v39, v156, s[44:45]
	v_cndmask_b32_e64 v37, v156, v37, s[44:45]
	v_cndmask_b32_e64 v145, v40, v41, s[42:43]
	v_cndmask_b32_e64 v147, v42, v43, s[42:43]
	s_nop 1
	v_mov_b32_dpp v146, v145 quad_perm:[1,0,3,2] row_mask:0xf bank_mask:0xf
	v_mov_b32_dpp v156, v147 quad_perm:[1,0,3,2] row_mask:0xf bank_mask:0xf
	v_cndmask_b32_e64 v41, v41, v146, s[42:43]
	v_cndmask_b32_e64 v40, v146, v40, s[42:43]
	v_cndmask_b32_e64 v43, v43, v156, s[42:43]
	v_cndmask_b32_e64 v42, v156, v42, s[42:43]
	v_cndmask_b32_e64 v145, v40, v42, s[44:45]
	v_cndmask_b32_e64 v147, v41, v43, s[44:45]
	s_nop 1
	v_mov_b32_dpp v146, v145 quad_perm:[2,3,0,1] row_mask:0xf bank_mask:0xf
	v_mov_b32_dpp v156, v147 quad_perm:[2,3,0,1] row_mask:0xf bank_mask:0xf
	v_cndmask_b32_e64 v42, v42, v146, s[44:45]
	v_cndmask_b32_e64 v40, v146, v40, s[44:45]
	v_cndmask_b32_e64 v43, v43, v156, s[44:45]
	v_cndmask_b32_e64 v41, v156, v41, s[44:45]
	v_cndmask_b32_e64 v145, v44, v45, s[42:43]
	v_cndmask_b32_e64 v147, v46, v47, s[42:43]
	s_nop 1
	v_mov_b32_dpp v146, v145 quad_perm:[1,0,3,2] row_mask:0xf bank_mask:0xf
	v_mov_b32_dpp v156, v147 quad_perm:[1,0,3,2] row_mask:0xf bank_mask:0xf
	v_cndmask_b32_e64 v45, v45, v146, s[42:43]
	v_cndmask_b32_e64 v44, v146, v44, s[42:43]
	v_cndmask_b32_e64 v47, v47, v156, s[42:43]
	v_cndmask_b32_e64 v46, v156, v46, s[42:43]
	v_cndmask_b32_e64 v145, v44, v46, s[44:45]
	v_cndmask_b32_e64 v147, v45, v47, s[44:45]
	s_nop 1
	v_mov_b32_dpp v146, v145 quad_perm:[2,3,0,1] row_mask:0xf bank_mask:0xf
	v_mov_b32_dpp v156, v147 quad_perm:[2,3,0,1] row_mask:0xf bank_mask:0xf
	v_cndmask_b32_e64 v46, v46, v146, s[44:45]
	v_cndmask_b32_e64 v44, v146, v44, s[44:45]
	v_cndmask_b32_e64 v47, v47, v156, s[44:45]
	v_cndmask_b32_e64 v45, v156, v45, s[44:45]
	v_cndmask_b32_e64 v145, v48, v49, s[42:43]
	v_cndmask_b32_e64 v147, v50, v51, s[42:43]
	s_nop 1
	v_mov_b32_dpp v146, v145 quad_perm:[1,0,3,2] row_mask:0xf bank_mask:0xf
	v_mov_b32_dpp v156, v147 quad_perm:[1,0,3,2] row_mask:0xf bank_mask:0xf
	v_cndmask_b32_e64 v49, v49, v146, s[42:43]
	v_cndmask_b32_e64 v48, v146, v48, s[42:43]
	v_cndmask_b32_e64 v51, v51, v156, s[42:43]
; #define LDSBAR() do { asm volatile("s_waitcnt lgkmcnt(0)" ::: "memory"); __builtin_amdgcn_s_barrier(); asm volatile("" ::: "memory"); } while (0)
; __device__ __forceinline__ void hg_seq(const Frame& F, unsigned char* ws, const float* s0, float* sout, float* Og, int seq, bool sample, int vs_base, int nvs) {
;     ...
;     if (active) {
; #pragma unroll
;     for (int kb = 0; kb < 8; ++kb)
; #pragma unroll
;         for (int i = 0; i < 4; ++i) sout[((size_t)seq * 128 + 16 * kb + 4 * q + i) * 128 + 16 * vs + r] = S[kb][i];
;     }
;     LDSBAR();
	v_cndmask_b32_e64 v50, v156, v50, s[42:43]
	v_cndmask_b32_e64 v145, v48, v50, s[44:45]
	v_cndmask_b32_e64 v147, v49, v51, s[44:45]
	s_nop 1
	v_mov_b32_dpp v146, v145 quad_perm:[2,3,0,1] row_mask:0xf bank_mask:0xf
	v_mov_b32_dpp v156, v147 quad_perm:[2,3,0,1] row_mask:0xf bank_mask:0xf
	v_cndmask_b32_e64 v50, v50, v146, s[44:45]
	v_cndmask_b32_e64 v48, v146, v48, s[44:45]
	v_cndmask_b32_e64 v51, v51, v156, s[44:45]
	v_cndmask_b32_e64 v49, v156, v49, s[44:45]
	v_cndmask_b32_e64 v145, v52, v53, s[42:43]
	v_cndmask_b32_e64 v147, v54, v55, s[42:43]
	s_nop 1
	v_mov_b32_dpp v146, v145 quad_perm:[1,0,3,2] row_mask:0xf bank_mask:0xf
	v_mov_b32_dpp v156, v147 quad_perm:[1,0,3,2] row_mask:0xf bank_mask:0xf
	v_cndmask_b32_e64 v53, v53, v146, s[42:43]
	v_cndmask_b32_e64 v52, v146, v52, s[42:43]
	v_cndmask_b32_e64 v55, v55, v156, s[42:43]
	v_cndmask_b32_e64 v54, v156, v54, s[42:43]
	v_cndmask_b32_e64 v145, v52, v54, s[44:45]
	v_cndmask_b32_e64 v147, v53, v55, s[44:45]
	s_nop 1
	v_mov_b32_dpp v146, v145 quad_perm:[2,3,0,1] row_mask:0xf bank_mask:0xf
	v_mov_b32_dpp v156, v147 quad_perm:[2,3,0,1] row_mask:0xf bank_mask:0xf
	v_cndmask_b32_e64 v54, v54, v146, s[44:45]
	v_cndmask_b32_e64 v52, v146, v52, s[44:45]
	v_cndmask_b32_e64 v55, v55, v156, s[44:45]
	v_cndmask_b32_e64 v53, v156, v53, s[44:45]
	v_cndmask_b32_e64 v145, v56, v57, s[42:43]
	v_cndmask_b32_e64 v147, v58, v59, s[42:43]
	s_nop 1
	v_mov_b32_dpp v146, v145 quad_perm:[1,0,3,2] row_mask:0xf bank_mask:0xf
	v_mov_b32_dpp v156, v147 quad_perm:[1,0,3,2] row_mask:0xf bank_mask:0xf
	v_cndmask_b32_e64 v57, v57, v146, s[42:43]
	v_cndmask_b32_e64 v56, v146, v56, s[42:43]
	v_cndmask_b32_e64 v59, v59, v156, s[42:43]
	v_cndmask_b32_e64 v58, v156, v58, s[42:43]
	v_cndmask_b32_e64 v145, v56, v58, s[44:45]
	v_cndmask_b32_e64 v147, v57, v59, s[44:45]
	s_nop 1
	v_mov_b32_dpp v146, v145 quad_perm:[2,3,0,1] row_mask:0xf bank_mask:0xf
	v_mov_b32_dpp v156, v147 quad_perm:[2,3,0,1] row_mask:0xf bank_mask:0xf
	v_cndmask_b32_e64 v58, v58, v146, s[44:45]
	v_cndmask_b32_e64 v56, v146, v56, s[44:45]
	v_cndmask_b32_e64 v59, v59, v156, s[44:45]
	v_cndmask_b32_e64 v57, v156, v57, s[44:45]
	v_cndmask_b32_e64 v145, v60, v61, s[42:43]
	v_cndmask_b32_e64 v147, v62, v63, s[42:43]
	s_nop 1
	v_mov_b32_dpp v146, v145 quad_perm:[1,0,3,2] row_mask:0xf bank_mask:0xf
	v_mov_b32_dpp v156, v147 quad_perm:[1,0,3,2] row_mask:0xf bank_mask:0xf
	v_cndmask_b32_e64 v61, v61, v146, s[42:43]
	v_cndmask_b32_e64 v60, v146, v60, s[42:43]
	v_cndmask_b32_e64 v63, v63, v156, s[42:43]
	v_cndmask_b32_e64 v62, v156, v62, s[42:43]
	v_cndmask_b32_e64 v145, v60, v62, s[44:45]
	v_cndmask_b32_e64 v147, v61, v63, s[44:45]
	s_nop 1
	v_mov_b32_dpp v146, v145 quad_perm:[2,3,0,1] row_mask:0xf bank_mask:0xf
	v_mov_b32_dpp v156, v147 quad_perm:[2,3,0,1] row_mask:0xf bank_mask:0xf
	v_cndmask_b32_e64 v62, v62, v146, s[44:45]
	v_cndmask_b32_e64 v60, v146, v60, s[44:45]
	v_cndmask_b32_e64 v63, v63, v156, s[44:45]
	v_cndmask_b32_e64 v61, v156, v61, s[44:45]
	v_cndmask_b32_e64 v145, v64, v65, s[42:43]
	v_cndmask_b32_e64 v147, v66, v67, s[42:43]
	s_nop 1
	v_mov_b32_dpp v146, v145 quad_perm:[1,0,3,2] row_mask:0xf bank_mask:0xf
	v_mov_b32_dpp v156, v147 quad_perm:[1,0,3,2] row_mask:0xf bank_mask:0xf
	v_cndmask_b32_e64 v65, v65, v146, s[42:43]
	v_cndmask_b32_e64 v64, v146, v64, s[42:43]
	v_cndmask_b32_e64 v67, v67, v156, s[42:43]
	v_cndmask_b32_e64 v66, v156, v66, s[42:43]
	v_cndmask_b32_e64 v145, v64, v66, s[44:45]
	v_cndmask_b32_e64 v147, v65, v67, s[44:45]
	s_nop 1
	v_mov_b32_dpp v146, v145 quad_perm:[2,3,0,1] row_mask:0xf bank_mask:0xf
	v_mov_b32_dpp v156, v147 quad_perm:[2,3,0,1] row_mask:0xf bank_mask:0xf
	v_cndmask_b32_e64 v66, v66, v146, s[44:45]
	v_cndmask_b32_e64 v64, v146, v64, s[44:45]
	v_cndmask_b32_e64 v67, v67, v156, s[44:45]
	v_cndmask_b32_e64 v65, v156, v65, s[44:45]
	global_store_dwordx4 v200, v[36:39], s[10:11]
	global_store_dwordx4 v201, v[40:43], s[10:11]
	global_store_dwordx4 v202, v[44:47], s[10:11]
	global_store_dwordx4 v203, v[48:51], s[10:11]
	global_store_dwordx4 v204, v[52:55], s[10:11]
	global_store_dwordx4 v205, v[56:59], s[10:11]
	global_store_dwordx4 v206, v[60:63], s[10:11]
	global_store_dwordx4 v207, v[64:67], s[10:11]
	s_add_u32 s10, s10, s34
	s_addc_u32 s11, s11, 0
	s_waitcnt lgkmcnt(0)
	s_barrier
	s_branch .LBB0_1245

; #define LDSBAR() do { asm volatile("s_waitcnt lgkmcnt(0)" ::: "memory"); __builtin_amdgcn_s_barrier(); asm volatile("" ::: "memory"); } while (0)
; #define HG_STORE(R, s) do { LAS unsigned char* d_ = ring + (s) * HG_SLOT; *(LAS v4u*)(d_ + 16 * tid) = R.q; if (vload) *(LAS v4u*)(d_ + 16384 + 16 * tid) = R.v; *(LAS v4u*)(d_ + 8192 + 16 * tid) = R.l0; \
;         if (tid < 160) *(LAS v4u*)(d_ + 24576 + 16 * tid) = R.l1; } while (0)
; __device__ __forceinline__ void hg_seq(const Frame& F, unsigned char* ws, const float* s0, float* sout, float* Og, int seq, bool sample, int vs_base, int nvs) {
;     ...
;     if (!sample) { const int b = seq >> 2; h = seq & 3; t0 = b * 2048; nch = 64; nvalid = 32; const size_t e0 = (size_t)t0 * DA + h * 128;
;         qf = ws + WS_Q + e0 * 2; vf = ws + WS_V + e0 * 2; lf = ws + WS_LOGF + e0 * 4; qp = 1024; lp = 2048; qstep = 32 * 1024; lstep = 32 * 2048; }
;     else { const int b = seq >> 2; h = seq & 3; t0 = TP + b * 8; nch = 1; nvalid = 8; const unsigned char* base = (const unsigned char*)sout + (size_t)seq * 65536;
;         qf = base; vf = base + 8192; lf = base + 16384; qp = 256; lp = 512; qstep = 0; lstep = 0; }
;     const size_t offq = (size_t)(tid >> 4) * qp + (tid & 15) * 16, offl0 = (size_t)(tid >> 5) * lp + (tid & 31) * 16, offl1 = (size_t)(16 + (tid >> 5)) * lp + (tid & 31) * 16, offl1c = tid < 160 ? offl1 : offl0;
;     {
;     f32x4 S[8];
;     if (sample && active) {
; #pragma unroll
;         for (int kb = 0; kb < 8; ++kb)
; #pragma unroll
;             for (int i = 0; i < 4; ++i) S[kb][i] = s0[((size_t)seq * 128 + 16 * kb + 4 * q + i) * 128 + 16 * vs + r];
;     } else {
; #pragma unroll
;         for (int kb = 0; kb < 8; ++kb) S[kb] = (f32x4){0.f, 0.f, 0.f, 0.f};
;     }
;     float* Ob = Og + (size_t)t0 * DA + h * 128;
;     ...
;     HgPre R0, R1, R2, R3, R4, R5;
;     R0.l1 = R0.v = (v4u){0u, 0u, 0u, 0u}; R1.l1 = R1.v = (v4u){0u, 0u, 0u, 0u}; R2.l1 = R2.v = (v4u){0u, 0u, 0u, 0u}; R3.l1 = R3.v = (v4u){0u, 0u, 0u, 0u}; R4.l1 = R4.v = (v4u){0u, 0u, 0u, 0u}; R5.l1 = R5.v = (v4u){0u, 0u, 0u, 0u};
;     HG_LOAD(R0, 0); HG_LOAD(R1, 1); HG_LOAD(R2, 2); HG_LOAD(R3, 3); HG_LOAD(R4, 4);
;     HG_STORE(R0, 0); LDSBAR();
.LBB0_1193:
	s_mov_b64 exec, -1
	s_waitcnt lgkmcnt(0)
	s_barrier
	s_load_dwordx2 s[16:17], s[0:1], 0x10
	s_sub_i32 s46, s2, 0x80
	s_mov_b64 exec, -1
	s_waitcnt lgkmcnt(0)
	s_lshl_b32 s3, s46, 16
	s_add_u32 s8, s16, s3
	s_addc_u32 s9, s17, 0
	s_add_u32 s10, s20, 0x4608000
	s_addc_u32 s11, s21, 0
	s_add_u32 s10, s10, s3
	s_addc_u32 s11, s11, 0
	s_lshr_b32 s6, s46, 2
	s_lshl_b32 s6, s6, 14
	s_and_b32 s7, s46, 3
	s_lshl_b32 s7, s7, 9
	s_add_i32 s6, s6, s7
	s_add_u32 s12, s22, 0x4080000
	s_addc_u32 s13, s23, 0
	s_add_u32 s12, s12, s6
	s_addc_u32 s13, s13, 0
	s_add_u32 s8, s8, 0x1000000
	s_addc_u32 s9, s9, 0
	s_add_u32 s10, s10, 0x1000000
	s_addc_u32 s11, s11, 0
	s_add_u32 s12, s12, 0x100000
	s_addc_u32 s13, s13, 0
	s_mov_b32 s34, 0x800000
	s_mov_b32 s35, 0
	v_lshlrev_b32_e32 v142, 4, v189
	s_lshl_b32 s3, s50, 10
	v_add_u32_e32 v143, s3, v142
	v_lshrrev_b32_e32 v1, 4, v189
	v_lshlrev_b32_e32 v144, 4, v1
	s_lshl_b32 s3, s50, 4
	v_and_b32_e32 v2, 15, v189
	v_add_u32_e32 v2, s3, v2
	v_lshlrev_b32_e32 v2, 2, v2
	v_lshl_add_u32 v208, v1, 13, v2
	v_add_u32_e32 v209, 0x1000, v208
	v_and_b32_e32 v3, 3, v189
	v_lshlrev_b32_e32 v3, 9, v3
	v_lshl_add_u32 v3, v1, 11, v3
	v_bfe_u32 v200, v189, 2, 2
	v_lshl_add_u32 v3, v200, 4, v3
	s_lshl_b32 s3, s50, 6
	v_add_u32_e32 v200, s3, v3
	v_add_u32_e32 v201, 0x2000, v200
	v_add_u32_e32 v202, 0x4000, v200
	v_add_u32_e32 v203, 0x6000, v200
	v_add_u32_e32 v204, 0x8000, v200
	v_add_u32_e32 v205, 0xa000, v200
	v_add_u32_e32 v206, 0xc000, v200
	v_add_u32_e32 v207, 0xe000, v200
	s_mov_b32 s42, 0x55555555
	s_mov_b32 s43, 0x55555555
	s_mov_b32 s44, 0x33333333
	s_mov_b32 s45, 0x33333333
	v_mov_b32_e32 v3, 0
	v_mov_b32_e32 v2, v143
	v_lshl_add_u64 v[210:211], s[10:11], 0, v[2:3]
	s_add_u32 s6, s10, 0x2000
	s_addc_u32 s7, s11, 0
	v_lshl_add_u64 v[212:213], s[6:7], 0, v[2:3]
	s_add_u32 s6, s10, 0x4000
	s_addc_u32 s7, s11, 0
	v_lshl_add_u64 v[214:215], s[6:7], 0, v[2:3]
	s_mov_b32 s36, 0
	s_lshl_b32 s37, s50, 10
	s_cmp_lt_u32 s50, 3
	s_cbranch_scc0 .Lsmpb_p4_done
	s_movk_i32 s36, 0x6000
	s_add_i32 s37, s37, 0x6000
.Lsmpb_p4_done:
	s_add_u32 s6, s10, s36
	s_addc_u32 s7, s11, 0
	v_lshl_add_u64 v[140:141], s[6:7], 0, v[2:3]
	s_lshl_b32 s38, s50, 10
	s_add_i32 s39, s38, 0x4000
	s_add_i32 s40, s38, 0x2000
	s_mov_b32 m0, s38
	s_nop 0
	global_load_lds_dwordx4 v[210:211], off
	s_mov_b32 m0, s39
	s_nop 0
	global_load_lds_dwordx4 v[212:213], off
	s_mov_b32 m0, s40
	s_nop 0
	global_load_lds_dwordx4 v[214:215], off
	s_mov_b32 m0, s37
	s_nop 0
	global_load_lds_dwordx4 v[140:141], off
	v_lshl_add_u64 v[210:211], v[210:211], 0, s[34:35]
	v_lshl_add_u64 v[212:213], v[212:213], 0, s[34:35]
	v_lshl_add_u64 v[214:215], v[214:215], 0, s[34:35]
	v_lshl_add_u64 v[140:141], v[140:141], 0, s[34:35]
	s_add_i32 m0, s38, 0x6c00
	s_nop 0
	global_load_lds_dwordx4 v[210:211], off
	s_add_i32 m0, s39, 0x6c00
	s_nop 0
	global_load_lds_dwordx4 v[212:213], off
	s_add_i32 m0, s40, 0x6c00
	s_nop 0
	global_load_lds_dwordx4 v[214:215], off
	s_add_i32 m0, s37, 0x6c00
	s_nop 0
	global_load_lds_dwordx4 v[140:141], off
	global_load_dwordx4 v[4:7], v200, s[8:9]
	global_load_dwordx4 v[8:11], v201, s[8:9]
	global_load_dwordx4 v[12:15], v202, s[8:9]
	global_load_dwordx4 v[16:19], v203, s[8:9]
	global_load_dwordx4 v[20:23], v204, s[8:9]
	global_load_dwordx4 v[24:27], v205, s[8:9]
	global_load_dwordx4 v[28:31], v206, s[8:9]
	global_load_dwordx4 v[32:35], v207, s[8:9]
	s_add_u32 s8, s8, s34
	s_addc_u32 s9, s9, 0
	global_load_dwordx4 v[36:39], v200, s[8:9]
	global_load_dwordx4 v[40:43], v201, s[8:9]
	global_load_dwordx4 v[44:47], v202, s[8:9]
	global_load_dwordx4 v[48:51], v203, s[8:9]
	global_load_dwordx4 v[52:55], v204, s[8:9]
	global_load_dwordx4 v[56:59], v205, s[8:9]
	global_load_dwordx4 v[60:63], v206, s[8:9]
	global_load_dwordx4 v[64:67], v207, s[8:9]
	s_add_u32 s8, s8, s34
	s_addc_u32 s9, s9, 0
	s_waitcnt vmcnt(8)
	s_barrier
	v_cndmask_b32_e64 v145, v4, v5, s[42:43]
	v_cndmask_b32_e64 v147, v6, v7, s[42:43]
	s_nop 1
	v_mov_b32_dpp v146, v145 quad_perm:[1,0,3,2] row_mask:0xf bank_mask:0xf
	v_mov_b32_dpp v156, v147 quad_perm:[1,0,3,2] row_mask:0xf bank_mask:0xf
	v_cndmask_b32_e64 v5, v5, v146, s[42:43]
	v_cndmask_b32_e64 v4, v146, v4, s[42:43]
	v_cndmask_b32_e64 v7, v7, v156, s[42:43]
	v_cndmask_b32_e64 v6, v156, v6, s[42:43]
	v_cndmask_b32_e64 v145, v4, v6, s[44:45]
	v_cndmask_b32_e64 v147, v5, v7, s[44:45]
	s_nop 1
	v_mov_b32_dpp v146, v145 quad_perm:[2,3,0,1] row_mask:0xf bank_mask:0xf
	v_mov_b32_dpp v156, v147 quad_perm:[2,3,0,1] row_mask:0xf bank_mask:0xf
	v_cndmask_b32_e64 v6, v6, v146, s[44:45]
	v_cndmask_b32_e64 v4, v146, v4, s[44:45]
	v_cndmask_b32_e64 v7, v7, v156, s[44:45]
	v_cndmask_b32_e64 v5, v156, v5, s[44:45]
	v_cndmask_b32_e64 v145, v8, v9, s[42:43]
	v_cndmask_b32_e64 v147, v10, v11, s[42:43]
	s_nop 1
	v_mov_b32_dpp v146, v145 quad_perm:[1,0,3,2] row_mask:0xf bank_mask:0xf
	v_mov_b32_dpp v156, v147 quad_perm:[1,0,3,2] row_mask:0xf bank_mask:0xf
	v_cndmask_b32_e64 v9, v9, v146, s[42:43]
	v_cndmask_b32_e64 v8, v146, v8, s[42:43]
	v_cndmask_b32_e64 v11, v11, v156, s[42:43]
	v_cndmask_b32_e64 v10, v156, v10, s[42:43]
	v_cndmask_b32_e64 v145, v8, v10, s[44:45]
	v_cndmask_b32_e64 v147, v9, v11, s[44:45]
	s_nop 1
	v_mov_b32_dpp v146, v145 quad_perm:[2,3,0,1] row_mask:0xf bank_mask:0xf
	v_mov_b32_dpp v156, v147 quad_perm:[2,3,0,1] row_mask:0xf bank_mask:0xf
	v_cndmask_b32_e64 v10, v10, v146, s[44:45]
	v_cndmask_b32_e64 v8, v146, v8, s[44:45]
	v_cndmask_b32_e64 v11, v11, v156, s[44:45]
	v_cndmask_b32_e64 v9, v156, v9, s[44:45]
	v_cndmask_b32_e64 v145, v12, v13, s[42:43]
	v_cndmask_b32_e64 v147, v14, v15, s[42:43]
	s_nop 1
	v_mov_b32_dpp v146, v145 quad_perm:[1,0,3,2] row_mask:0xf bank_mask:0xf
; #define LAS __attribute__((address_space(3)))
; __device__ __forceinline__ unsigned pk2(float lo, float hi) { const f32x2_t_ v = {lo, hi}; return __builtin_bit_cast(unsigned, __builtin_convertvector(v, bf16x2_t_)); }
; __device__ __forceinline__ void hg_chunk(const LAS unsigned char* sl, f32x4 (&S)[8], float* Orow, int nvalid, int vs, int lane) {
;     const int r = lane & 15, q = lane >> 4;
;     const bf16x8 vfr = *(const LAS bf16x8*)(sl + 16384 + ((vs * 64 + lane) << 4));
;     f32x4 o0 = {0.f, 0.f, 0.f, 0.f}, o1 = {0.f, 0.f, 0.f, 0.f};
;     { const bf16x8 s0 = *(const LAS bf16x8*)(sl + 24576 + (lane << 4)), s1 = *(const LAS bf16x8*)(sl + 24576 + ((64 + lane) << 4));
;       o0 = __builtin_amdgcn_mfma_f32_16x16x32_bf16(s0, vfr, o0, 0, 0, 0); o1 = __builtin_amdgcn_mfma_f32_16x16x32_bf16(s1, vfr, o1, 0, 0, 0); }
; #pragma unroll
;     for (int m = 0; m < 4; ++m) {
;         v4u sw; sw.x = pk2(S[2 * m][0], S[2 * m][1]); sw.y = pk2(S[2 * m][2], S[2 * m][3]); sw.z = pk2(S[2 * m + 1][0], S[2 * m + 1][1]); sw.w = pk2(S[2 * m + 1][2], S[2 * m + 1][3]);
;         const bf16x8 sb = __builtin_bit_cast(bf16x8, sw);
;         const bf16x8 a0 = *(const LAS bf16x8*)(sl + ((m * 64 + lane) << 4)), a1 = *(const LAS bf16x8*)(sl + (((4 + m) * 64 + lane) << 4));
; __device__ __forceinline__ void hg_seq(const Frame& F, unsigned char* ws, const float* s0, float* sout, float* Og, int seq, bool sample, int vs_base, int nvs) {
;     ...
;     if (sample && active) {
; #pragma unroll
;         for (int kb = 0; kb < 8; ++kb)
; #pragma unroll
;             for (int i = 0; i < 4; ++i) S[kb][i] = s0[((size_t)seq * 128 + 16 * kb + 4 * q + i) * 128 + 16 * vs + r];
;     } else {
	v_mov_b32_dpp v156, v147 quad_perm:[1,0,3,2] row_mask:0xf bank_mask:0xf
	v_cndmask_b32_e64 v13, v13, v146, s[42:43]
	v_cndmask_b32_e64 v12, v146, v12, s[42:43]
	v_cndmask_b32_e64 v15, v15, v156, s[42:43]
	v_cndmask_b32_e64 v14, v156, v14, s[42:43]
	v_cndmask_b32_e64 v145, v12, v14, s[44:45]
	v_cndmask_b32_e64 v147, v13, v15, s[44:45]
	s_nop 1
	v_mov_b32_dpp v146, v145 quad_perm:[2,3,0,1] row_mask:0xf bank_mask:0xf
	v_mov_b32_dpp v156, v147 quad_perm:[2,3,0,1] row_mask:0xf bank_mask:0xf
	v_cndmask_b32_e64 v14, v14, v146, s[44:45]
	v_cndmask_b32_e64 v12, v146, v12, s[44:45]
	v_cndmask_b32_e64 v15, v15, v156, s[44:45]
	v_cndmask_b32_e64 v13, v156, v13, s[44:45]
	v_cndmask_b32_e64 v145, v16, v17, s[42:43]
	v_cndmask_b32_e64 v147, v18, v19, s[42:43]
	s_nop 1
	v_mov_b32_dpp v146, v145 quad_perm:[1,0,3,2] row_mask:0xf bank_mask:0xf
	v_mov_b32_dpp v156, v147 quad_perm:[1,0,3,2] row_mask:0xf bank_mask:0xf
	v_cndmask_b32_e64 v17, v17, v146, s[42:43]
	v_cndmask_b32_e64 v16, v146, v16, s[42:43]
	v_cndmask_b32_e64 v19, v19, v156, s[42:43]
	v_cndmask_b32_e64 v18, v156, v18, s[42:43]
	v_cndmask_b32_e64 v145, v16, v18, s[44:45]
	v_cndmask_b32_e64 v147, v17, v19, s[44:45]
	s_nop 1
	v_mov_b32_dpp v146, v145 quad_perm:[2,3,0,1] row_mask:0xf bank_mask:0xf
	v_mov_b32_dpp v156, v147 quad_perm:[2,3,0,1] row_mask:0xf bank_mask:0xf
	v_cndmask_b32_e64 v18, v18, v146, s[44:45]
	v_cndmask_b32_e64 v16, v146, v16, s[44:45]
	v_cndmask_b32_e64 v19, v19, v156, s[44:45]
	v_cndmask_b32_e64 v17, v156, v17, s[44:45]
	v_cndmask_b32_e64 v145, v20, v21, s[42:43]
	v_cndmask_b32_e64 v147, v22, v23, s[42:43]
	s_nop 1
	v_mov_b32_dpp v146, v145 quad_perm:[1,0,3,2] row_mask:0xf bank_mask:0xf
	v_mov_b32_dpp v156, v147 quad_perm:[1,0,3,2] row_mask:0xf bank_mask:0xf
	v_cndmask_b32_e64 v21, v21, v146, s[42:43]
	v_cndmask_b32_e64 v20, v146, v20, s[42:43]
	v_cndmask_b32_e64 v23, v23, v156, s[42:43]
	v_cndmask_b32_e64 v22, v156, v22, s[42:43]
	v_cndmask_b32_e64 v145, v20, v22, s[44:45]
	v_cndmask_b32_e64 v147, v21, v23, s[44:45]
	s_nop 1
	v_mov_b32_dpp v146, v145 quad_perm:[2,3,0,1] row_mask:0xf bank_mask:0xf
	v_mov_b32_dpp v156, v147 quad_perm:[2,3,0,1] row_mask:0xf bank_mask:0xf
	v_cndmask_b32_e64 v22, v22, v146, s[44:45]
	v_cndmask_b32_e64 v20, v146, v20, s[44:45]
	v_cndmask_b32_e64 v23, v23, v156, s[44:45]
	v_cndmask_b32_e64 v21, v156, v21, s[44:45]
	v_cndmask_b32_e64 v145, v24, v25, s[42:43]
	v_cndmask_b32_e64 v147, v26, v27, s[42:43]
	s_nop 1
	v_mov_b32_dpp v146, v145 quad_perm:[1,0,3,2] row_mask:0xf bank_mask:0xf
	v_mov_b32_dpp v156, v147 quad_perm:[1,0,3,2] row_mask:0xf bank_mask:0xf
	v_cndmask_b32_e64 v25, v25, v146, s[42:43]
	v_cndmask_b32_e64 v24, v146, v24, s[42:43]
	v_cndmask_b32_e64 v27, v27, v156, s[42:43]
	v_cndmask_b32_e64 v26, v156, v26, s[42:43]
	v_cndmask_b32_e64 v145, v24, v26, s[44:45]
	v_cndmask_b32_e64 v147, v25, v27, s[44:45]
	s_nop 1
	v_mov_b32_dpp v146, v145 quad_perm:[2,3,0,1] row_mask:0xf bank_mask:0xf
	v_mov_b32_dpp v156, v147 quad_perm:[2,3,0,1] row_mask:0xf bank_mask:0xf
	v_cndmask_b32_e64 v26, v26, v146, s[44:45]
	v_cndmask_b32_e64 v24, v146, v24, s[44:45]
	v_cndmask_b32_e64 v27, v27, v156, s[44:45]
	v_cndmask_b32_e64 v25, v156, v25, s[44:45]
	v_cndmask_b32_e64 v145, v28, v29, s[42:43]
	v_cndmask_b32_e64 v147, v30, v31, s[42:43]
	s_nop 1
	v_mov_b32_dpp v146, v145 quad_perm:[1,0,3,2] row_mask:0xf bank_mask:0xf
	v_mov_b32_dpp v156, v147 quad_perm:[1,0,3,2] row_mask:0xf bank_mask:0xf
	v_cndmask_b32_e64 v29, v29, v146, s[42:43]
	v_cndmask_b32_e64 v28, v146, v28, s[42:43]
	v_cndmask_b32_e64 v31, v31, v156, s[42:43]
	v_cndmask_b32_e64 v30, v156, v30, s[42:43]
	v_cndmask_b32_e64 v145, v28, v30, s[44:45]
	v_cndmask_b32_e64 v147, v29, v31, s[44:45]
	s_nop 1
	v_mov_b32_dpp v146, v145 quad_perm:[2,3,0,1] row_mask:0xf bank_mask:0xf
	v_mov_b32_dpp v156, v147 quad_perm:[2,3,0,1] row_mask:0xf bank_mask:0xf
	v_cndmask_b32_e64 v30, v30, v146, s[44:45]
	v_cndmask_b32_e64 v28, v146, v28, s[44:45]
	v_cndmask_b32_e64 v31, v31, v156, s[44:45]
	v_cndmask_b32_e64 v29, v156, v29, s[44:45]
	v_cndmask_b32_e64 v145, v32, v33, s[42:43]
	v_cndmask_b32_e64 v147, v34, v35, s[42:43]
	s_nop 1
	v_mov_b32_dpp v146, v145 quad_perm:[1,0,3,2] row_mask:0xf bank_mask:0xf
	v_mov_b32_dpp v156, v147 quad_perm:[1,0,3,2] row_mask:0xf bank_mask:0xf
	v_cndmask_b32_e64 v33, v33, v146, s[42:43]
	v_cndmask_b32_e64 v32, v146, v32, s[42:43]
	v_cndmask_b32_e64 v35, v35, v156, s[42:43]
	v_cndmask_b32_e64 v34, v156, v34, s[42:43]
	v_cndmask_b32_e64 v145, v32, v34, s[44:45]
	v_cndmask_b32_e64 v147, v33, v35, s[44:45]
	s_nop 1
	v_mov_b32_dpp v146, v145 quad_perm:[2,3,0,1] row_mask:0xf bank_mask:0xf
	v_mov_b32_dpp v156, v147 quad_perm:[2,3,0,1] row_mask:0xf bank_mask:0xf
	v_cndmask_b32_e64 v34, v34, v146, s[44:45]
	v_cndmask_b32_e64 v32, v146, v32, s[44:45]
	v_cndmask_b32_e64 v35, v35, v156, s[44:45]
	v_cndmask_b32_e64 v33, v156, v33, s[44:45]
	v_mov_b32_e32 v1, v142
	v_mov_b32_e32 v2, v143
	v_mov_b32_e32 v3, v144
	ds_read_b128 v[164:167], v3 offset:26624
	ds_read_b128 v[168:171], v3 offset:26688
	ds_read_b128 v[172:175], v3 offset:26752
	ds_read_b128 v[176:179], v3 offset:26816
	ds_read_b128 v[180:183], v3 offset:26880
	ds_read_b128 v[184:187], v3 offset:26944
	ds_read_b128 v[148:151], v3 offset:27008
	ds_read_b128 v[152:155], v3 offset:27072
	ds_read_b128 v[84:87], v2 offset:16384
	ds_read_b128 v[88:91], v1 offset:24576
	ds_read_b128 v[92:95], v1 offset:0
	ds_read_b128 v[96:99], v1 offset:1024
	ds_read_b128 v[100:103], v1 offset:2048
	ds_read_b128 v[104:107], v1 offset:3072
	v_cvt_pk_bf16_f32 v68, v4, v5
	v_cvt_pk_bf16_f32 v69, v6, v7
	v_cvt_pk_bf16_f32 v70, v8, v9
	v_cvt_pk_bf16_f32 v71, v10, v11
	v_cvt_pk_bf16_f32 v72, v12, v13
	v_cvt_pk_bf16_f32 v73, v14, v15
	v_cvt_pk_bf16_f32 v74, v16, v17
	v_cvt_pk_bf16_f32 v75, v18, v19
	v_cvt_pk_bf16_f32 v76, v20, v21
	v_cvt_pk_bf16_f32 v77, v22, v23
	v_cvt_pk_bf16_f32 v78, v24, v25
	v_cvt_pk_bf16_f32 v79, v26, v27
	v_cvt_pk_bf16_f32 v80, v28, v29
	v_cvt_pk_bf16_f32 v81, v30, v31
	v_cvt_pk_bf16_f32 v82, v32, v33
	v_cvt_pk_bf16_f32 v83, v34, v35
	s_waitcnt lgkmcnt(6)
; #define LAS __attribute__((address_space(3)))
; __device__ __forceinline__ unsigned pk2(float lo, float hi) { const f32x2_t_ v = {lo, hi}; return __builtin_bit_cast(unsigned, __builtin_convertvector(v, bf16x2_t_)); }
; __device__ __forceinline__ void hg_chunk(const LAS unsigned char* sl, f32x4 (&S)[8], float* Orow, int nvalid, int vs, int lane) {
;     const int r = lane & 15, q = lane >> 4;
;     const bf16x8 vfr = *(const LAS bf16x8*)(sl + 16384 + ((vs * 64 + lane) << 4));
;     f32x4 o0 = {0.f, 0.f, 0.f, 0.f}, o1 = {0.f, 0.f, 0.f, 0.f};
;     { const bf16x8 s0 = *(const LAS bf16x8*)(sl + 24576 + (lane << 4)), s1 = *(const LAS bf16x8*)(sl + 24576 + ((64 + lane) << 4));
;       o0 = __builtin_amdgcn_mfma_f32_16x16x32_bf16(s0, vfr, o0, 0, 0, 0); o1 = __builtin_amdgcn_mfma_f32_16x16x32_bf16(s1, vfr, o1, 0, 0, 0); }
; #pragma unroll
;     for (int m = 0; m < 4; ++m) {
;         v4u sw; sw.x = pk2(S[2 * m][0], S[2 * m][1]); sw.y = pk2(S[2 * m][2], S[2 * m][3]); sw.z = pk2(S[2 * m + 1][0], S[2 * m + 1][1]); sw.w = pk2(S[2 * m + 1][2], S[2 * m + 1][3]);
;         const bf16x8 sb = __builtin_bit_cast(bf16x8, sw);
;         const bf16x8 a0 = *(const LAS bf16x8*)(sl + ((m * 64 + lane) << 4)), a1 = *(const LAS bf16x8*)(sl + (((4 + m) * 64 + lane) << 4));
;         o0 = __builtin_amdgcn_mfma_f32_16x16x32_bf16(a0, sb, o0, 0, 0, 0); o1 = __builtin_amdgcn_mfma_f32_16x16x32_bf16(a1, sb, o1, 0, 0, 0);
;     }
; #pragma unroll
;     for (int i = 0; i < 4; ++i) { const int c0 = 4 * q + i;
;         if (c0 < nvalid) Orow[(size_t)c0 * DA + 16 * vs + r] = o0[i];
;         if (c0 + 16 < nvalid) Orow[(size_t)(c0 + 16) * DA + 16 * vs + r] = o1[i]; }
; #pragma unroll
;     for (int kb = 0; kb < 8; ++kb) { const f32x4 d = *(const LAS f32x4*)(sl + 26624 + ((16 * kb + 4 * q) << 2));
;         const bf16x8 ke = *(const LAS bf16x8*)(sl + 8192 + ((kb * 64 + lane) << 4));
;         S[kb] = __builtin_amdgcn_mfma_f32_16x16x32_bf16(ke, vfr, S[kb] * d, 0, 0, 0); }
	v_pk_mul_f32 v[4:5], v[4:5], v[164:165]
	v_pk_mul_f32 v[6:7], v[6:7], v[166:167]
	v_pk_mul_f32 v[8:9], v[8:9], v[168:169]
	v_pk_mul_f32 v[10:11], v[10:11], v[170:171]
	v_pk_mul_f32 v[12:13], v[12:13], v[172:173]
	v_pk_mul_f32 v[14:15], v[14:15], v[174:175]
	v_pk_mul_f32 v[16:17], v[16:17], v[176:177]
	v_pk_mul_f32 v[18:19], v[18:19], v[178:179]
	v_pk_mul_f32 v[20:21], v[20:21], v[180:181]
	v_pk_mul_f32 v[22:23], v[22:23], v[182:183]
	v_pk_mul_f32 v[24:25], v[24:25], v[184:185]
	v_pk_mul_f32 v[26:27], v[26:27], v[186:187]
	v_pk_mul_f32 v[28:29], v[28:29], v[148:149]
	v_pk_mul_f32 v[30:31], v[30:31], v[150:151]
	v_pk_mul_f32 v[32:33], v[32:33], v[152:153]
	v_pk_mul_f32 v[34:35], v[34:35], v[154:155]
	ds_read_b128 v[108:111], v1 offset:8192
	ds_read_b128 v[112:115], v1 offset:9216
	ds_read_b128 v[116:119], v1 offset:10240
	ds_read_b128 v[120:123], v1 offset:11264
	ds_read_b128 v[124:127], v1 offset:12288
	ds_read_b128 v[128:131], v1 offset:13312
	ds_read_b128 v[132:135], v1 offset:14336
	ds_read_b128 v[136:139], v1 offset:15360
	s_waitcnt lgkmcnt(12)
	v_mfma_f32_16x16x32_bf16 v[196:199], v[88:91], v[84:87], 0
	s_waitcnt lgkmcnt(11)
	v_mfma_f32_16x16x32_bf16 v[196:199], v[92:95], v[68:71], v[196:199]
	s_waitcnt lgkmcnt(10)
	v_mfma_f32_16x16x32_bf16 v[196:199], v[96:99], v[72:75], v[196:199]
	s_waitcnt lgkmcnt(9)
	v_mfma_f32_16x16x32_bf16 v[196:199], v[100:103], v[76:79], v[196:199]
	s_waitcnt lgkmcnt(8)
	v_mfma_f32_16x16x32_bf16 v[196:199], v[104:107], v[80:83], v[196:199]
	s_waitcnt lgkmcnt(7)
	v_mfma_f32_16x16x32_bf16 v[4:7], v[108:111], v[84:87], v[4:7]
	s_waitcnt lgkmcnt(6)
	v_mfma_f32_16x16x32_bf16 v[8:11], v[112:115], v[84:87], v[8:11]
	s_waitcnt lgkmcnt(5)
	v_mfma_f32_16x16x32_bf16 v[12:15], v[116:119], v[84:87], v[12:15]
	s_waitcnt lgkmcnt(4)
	v_mfma_f32_16x16x32_bf16 v[16:19], v[120:123], v[84:87], v[16:19]
	s_waitcnt lgkmcnt(3)
	v_mfma_f32_16x16x32_bf16 v[20:23], v[124:127], v[84:87], v[20:23]
	s_waitcnt lgkmcnt(2)
	v_mfma_f32_16x16x32_bf16 v[24:27], v[128:131], v[84:87], v[24:27]
	s_waitcnt lgkmcnt(1)
	v_mfma_f32_16x16x32_bf16 v[28:31], v[132:135], v[84:87], v[28:31]
	s_waitcnt lgkmcnt(0)
	v_mfma_f32_16x16x32_bf16 v[32:35], v[136:139], v[84:87], v[32:35]
	s_mov_b32 exec_hi, 0
	global_store_dword v208, v196, s[12:13]
	global_store_dword v208, v197, s[12:13] offset:2048
	global_store_dword v209, v198, s[12:13]
	global_store_dword v209, v199, s[12:13] offset:2048
	s_mov_b64 exec, -1
	s_add_u32 s12, s12, 0x80000
	s_addc_u32 s13, s13, 0
	s_nop 7
	v_cndmask_b32_e64 v145, v4, v5, s[42:43]
	v_cndmask_b32_e64 v147, v6, v7, s[42:43]
	s_nop 1
	v_mov_b32_dpp v146, v145 quad_perm:[1,0,3,2] row_mask:0xf bank_mask:0xf
	v_mov_b32_dpp v156, v147 quad_perm:[1,0,3,2] row_mask:0xf bank_mask:0xf
	v_cndmask_b32_e64 v5, v5, v146, s[42:43]
	v_cndmask_b32_e64 v4, v146, v4, s[42:43]
	v_cndmask_b32_e64 v7, v7, v156, s[42:43]
	v_cndmask_b32_e64 v6, v156, v6, s[42:43]
	v_cndmask_b32_e64 v145, v4, v6, s[44:45]
	v_cndmask_b32_e64 v147, v5, v7, s[44:45]
	s_nop 1
	v_mov_b32_dpp v146, v145 quad_perm:[2,3,0,1] row_mask:0xf bank_mask:0xf
	v_mov_b32_dpp v156, v147 quad_perm:[2,3,0,1] row_mask:0xf bank_mask:0xf
	v_cndmask_b32_e64 v6, v6, v146, s[44:45]
	v_cndmask_b32_e64 v4, v146, v4, s[44:45]
	v_cndmask_b32_e64 v7, v7, v156, s[44:45]
	v_cndmask_b32_e64 v5, v156, v5, s[44:45]
	v_cndmask_b32_e64 v145, v8, v9, s[42:43]
	v_cndmask_b32_e64 v147, v10, v11, s[42:43]
	s_nop 1
	v_mov_b32_dpp v146, v145 quad_perm:[1,0,3,2] row_mask:0xf bank_mask:0xf
	v_mov_b32_dpp v156, v147 quad_perm:[1,0,3,2] row_mask:0xf bank_mask:0xf
	v_cndmask_b32_e64 v9, v9, v146, s[42:43]
	v_cndmask_b32_e64 v8, v146, v8, s[42:43]
	v_cndmask_b32_e64 v11, v11, v156, s[42:43]
	v_cndmask_b32_e64 v10, v156, v10, s[42:43]
	v_cndmask_b32_e64 v145, v8, v10, s[44:45]
	v_cndmask_b32_e64 v147, v9, v11, s[44:45]
	s_nop 1
	v_mov_b32_dpp v146, v145 quad_perm:[2,3,0,1] row_mask:0xf bank_mask:0xf
	v_mov_b32_dpp v156, v147 quad_perm:[2,3,0,1] row_mask:0xf bank_mask:0xf
	v_cndmask_b32_e64 v10, v10, v146, s[44:45]
	v_cndmask_b32_e64 v8, v146, v8, s[44:45]
	v_cndmask_b32_e64 v11, v11, v156, s[44:45]
	v_cndmask_b32_e64 v9, v156, v9, s[44:45]
	v_cndmask_b32_e64 v145, v12, v13, s[42:43]
	v_cndmask_b32_e64 v147, v14, v15, s[42:43]
	s_nop 1
	v_mov_b32_dpp v146, v145 quad_perm:[1,0,3,2] row_mask:0xf bank_mask:0xf
	v_mov_b32_dpp v156, v147 quad_perm:[1,0,3,2] row_mask:0xf bank_mask:0xf
	v_cndmask_b32_e64 v13, v13, v146, s[42:43]
	v_cndmask_b32_e64 v12, v146, v12, s[42:43]
	v_cndmask_b32_e64 v15, v15, v156, s[42:43]
	v_cndmask_b32_e64 v14, v156, v14, s[42:43]
	v_cndmask_b32_e64 v145, v12, v14, s[44:45]
	v_cndmask_b32_e64 v147, v13, v15, s[44:45]
	s_nop 1
	v_mov_b32_dpp v146, v145 quad_perm:[2,3,0,1] row_mask:0xf bank_mask:0xf
	v_mov_b32_dpp v156, v147 quad_perm:[2,3,0,1] row_mask:0xf bank_mask:0xf
	v_cndmask_b32_e64 v14, v14, v146, s[44:45]
	v_cndmask_b32_e64 v12, v146, v12, s[44:45]
	v_cndmask_b32_e64 v15, v15, v156, s[44:45]
	v_cndmask_b32_e64 v13, v156, v13, s[44:45]
	v_cndmask_b32_e64 v145, v16, v17, s[42:43]
	v_cndmask_b32_e64 v147, v18, v19, s[42:43]
	s_nop 1
	v_mov_b32_dpp v146, v145 quad_perm:[1,0,3,2] row_mask:0xf bank_mask:0xf
	v_mov_b32_dpp v156, v147 quad_perm:[1,0,3,2] row_mask:0xf bank_mask:0xf
	v_cndmask_b32_e64 v17, v17, v146, s[42:43]
	v_cndmask_b32_e64 v16, v146, v16, s[42:43]
	v_cndmask_b32_e64 v19, v19, v156, s[42:43]
	v_cndmask_b32_e64 v18, v156, v18, s[42:43]
	v_cndmask_b32_e64 v145, v16, v18, s[44:45]
	v_cndmask_b32_e64 v147, v17, v19, s[44:45]
	s_nop 1
	v_mov_b32_dpp v146, v145 quad_perm:[2,3,0,1] row_mask:0xf bank_mask:0xf
	v_mov_b32_dpp v156, v147 quad_perm:[2,3,0,1] row_mask:0xf bank_mask:0xf
; __device__ __forceinline__ void hg_seq(const Frame& F, unsigned char* ws, const float* s0, float* sout, float* Og, int seq, bool sample, int vs_base, int nvs) {
;     ...
;     if (sample && active) {
; #pragma unroll
;         for (int kb = 0; kb < 8; ++kb)
; #pragma unroll
;             for (int i = 0; i < 4; ++i) S[kb][i] = s0[((size_t)seq * 128 + 16 * kb + 4 * q + i) * 128 + 16 * vs + r];
;     } else {
;     ...
;     if (active) {
; #pragma unroll
;     for (int kb = 0; kb < 8; ++kb)
; #pragma unroll
;         for (int i = 0; i < 4; ++i) sout[((size_t)seq * 128 + 16 * kb + 4 * q + i) * 128 + 16 * vs + r] = S[kb][i];
;     }
	v_cndmask_b32_e64 v18, v18, v146, s[44:45]
	v_cndmask_b32_e64 v16, v146, v16, s[44:45]
	v_cndmask_b32_e64 v19, v19, v156, s[44:45]
	v_cndmask_b32_e64 v17, v156, v17, s[44:45]
	v_cndmask_b32_e64 v145, v20, v21, s[42:43]
	v_cndmask_b32_e64 v147, v22, v23, s[42:43]
	s_nop 1
	v_mov_b32_dpp v146, v145 quad_perm:[1,0,3,2] row_mask:0xf bank_mask:0xf
	v_mov_b32_dpp v156, v147 quad_perm:[1,0,3,2] row_mask:0xf bank_mask:0xf
	v_cndmask_b32_e64 v21, v21, v146, s[42:43]
	v_cndmask_b32_e64 v20, v146, v20, s[42:43]
	v_cndmask_b32_e64 v23, v23, v156, s[42:43]
	v_cndmask_b32_e64 v22, v156, v22, s[42:43]
	v_cndmask_b32_e64 v145, v20, v22, s[44:45]
	v_cndmask_b32_e64 v147, v21, v23, s[44:45]
	s_nop 1
	v_mov_b32_dpp v146, v145 quad_perm:[2,3,0,1] row_mask:0xf bank_mask:0xf
	v_mov_b32_dpp v156, v147 quad_perm:[2,3,0,1] row_mask:0xf bank_mask:0xf
	v_cndmask_b32_e64 v22, v22, v146, s[44:45]
	v_cndmask_b32_e64 v20, v146, v20, s[44:45]
	v_cndmask_b32_e64 v23, v23, v156, s[44:45]
	v_cndmask_b32_e64 v21, v156, v21, s[44:45]
	v_cndmask_b32_e64 v145, v24, v25, s[42:43]
	v_cndmask_b32_e64 v147, v26, v27, s[42:43]
	s_nop 1
	v_mov_b32_dpp v146, v145 quad_perm:[1,0,3,2] row_mask:0xf bank_mask:0xf
	v_mov_b32_dpp v156, v147 quad_perm:[1,0,3,2] row_mask:0xf bank_mask:0xf
	v_cndmask_b32_e64 v25, v25, v146, s[42:43]
	v_cndmask_b32_e64 v24, v146, v24, s[42:43]
	v_cndmask_b32_e64 v27, v27, v156, s[42:43]
	v_cndmask_b32_e64 v26, v156, v26, s[42:43]
	v_cndmask_b32_e64 v145, v24, v26, s[44:45]
	v_cndmask_b32_e64 v147, v25, v27, s[44:45]
	s_nop 1
	v_mov_b32_dpp v146, v145 quad_perm:[2,3,0,1] row_mask:0xf bank_mask:0xf
	v_mov_b32_dpp v156, v147 quad_perm:[2,3,0,1] row_mask:0xf bank_mask:0xf
	v_cndmask_b32_e64 v26, v26, v146, s[44:45]
	v_cndmask_b32_e64 v24, v146, v24, s[44:45]
	v_cndmask_b32_e64 v27, v27, v156, s[44:45]
	v_cndmask_b32_e64 v25, v156, v25, s[44:45]
	v_cndmask_b32_e64 v145, v28, v29, s[42:43]
	v_cndmask_b32_e64 v147, v30, v31, s[42:43]
	s_nop 1
	v_mov_b32_dpp v146, v145 quad_perm:[1,0,3,2] row_mask:0xf bank_mask:0xf
	v_mov_b32_dpp v156, v147 quad_perm:[1,0,3,2] row_mask:0xf bank_mask:0xf
	v_cndmask_b32_e64 v29, v29, v146, s[42:43]
	v_cndmask_b32_e64 v28, v146, v28, s[42:43]
	v_cndmask_b32_e64 v31, v31, v156, s[42:43]
	v_cndmask_b32_e64 v30, v156, v30, s[42:43]
	v_cndmask_b32_e64 v145, v28, v30, s[44:45]
	v_cndmask_b32_e64 v147, v29, v31, s[44:45]
	s_nop 1
	v_mov_b32_dpp v146, v145 quad_perm:[2,3,0,1] row_mask:0xf bank_mask:0xf
	v_mov_b32_dpp v156, v147 quad_perm:[2,3,0,1] row_mask:0xf bank_mask:0xf
	v_cndmask_b32_e64 v30, v30, v146, s[44:45]
	v_cndmask_b32_e64 v28, v146, v28, s[44:45]
	v_cndmask_b32_e64 v31, v31, v156, s[44:45]
	v_cndmask_b32_e64 v29, v156, v29, s[44:45]
	v_cndmask_b32_e64 v145, v32, v33, s[42:43]
	v_cndmask_b32_e64 v147, v34, v35, s[42:43]
	s_nop 1
	v_mov_b32_dpp v146, v145 quad_perm:[1,0,3,2] row_mask:0xf bank_mask:0xf
	v_mov_b32_dpp v156, v147 quad_perm:[1,0,3,2] row_mask:0xf bank_mask:0xf
	v_cndmask_b32_e64 v33, v33, v146, s[42:43]
	v_cndmask_b32_e64 v32, v146, v32, s[42:43]
	v_cndmask_b32_e64 v35, v35, v156, s[42:43]
	v_cndmask_b32_e64 v34, v156, v34, s[42:43]
	v_cndmask_b32_e64 v145, v32, v34, s[44:45]
	v_cndmask_b32_e64 v147, v33, v35, s[44:45]
	s_nop 1
	v_mov_b32_dpp v146, v145 quad_perm:[2,3,0,1] row_mask:0xf bank_mask:0xf
	v_mov_b32_dpp v156, v147 quad_perm:[2,3,0,1] row_mask:0xf bank_mask:0xf
	v_cndmask_b32_e64 v34, v34, v146, s[44:45]
	v_cndmask_b32_e64 v32, v146, v32, s[44:45]
	v_cndmask_b32_e64 v35, v35, v156, s[44:45]
	v_cndmask_b32_e64 v33, v156, v33, s[44:45]
	global_store_dwordx4 v200, v[4:7], s[10:11]
	global_store_dwordx4 v201, v[8:11], s[10:11]
	global_store_dwordx4 v202, v[12:15], s[10:11]
	global_store_dwordx4 v203, v[16:19], s[10:11]
	global_store_dwordx4 v204, v[20:23], s[10:11]
	global_store_dwordx4 v205, v[24:27], s[10:11]
	global_store_dwordx4 v206, v[28:31], s[10:11]
	global_store_dwordx4 v207, v[32:35], s[10:11]
	s_add_u32 s10, s10, s34
	s_addc_u32 s11, s11, 0
	s_waitcnt vmcnt(12)
	v_cndmask_b32_e64 v145, v36, v37, s[42:43]
	v_cndmask_b32_e64 v147, v38, v39, s[42:43]
	s_nop 1
	v_mov_b32_dpp v146, v145 quad_perm:[1,0,3,2] row_mask:0xf bank_mask:0xf
	v_mov_b32_dpp v156, v147 quad_perm:[1,0,3,2] row_mask:0xf bank_mask:0xf
	v_cndmask_b32_e64 v37, v37, v146, s[42:43]
	v_cndmask_b32_e64 v36, v146, v36, s[42:43]
	v_cndmask_b32_e64 v39, v39, v156, s[42:43]
	v_cndmask_b32_e64 v38, v156, v38, s[42:43]
	v_cndmask_b32_e64 v145, v36, v38, s[44:45]
	v_cndmask_b32_e64 v147, v37, v39, s[44:45]
	s_nop 1
	v_mov_b32_dpp v146, v145 quad_perm:[2,3,0,1] row_mask:0xf bank_mask:0xf
	v_mov_b32_dpp v156, v147 quad_perm:[2,3,0,1] row_mask:0xf bank_mask:0xf
	v_cndmask_b32_e64 v38, v38, v146, s[44:45]
	v_cndmask_b32_e64 v36, v146, v36, s[44:45]
	v_cndmask_b32_e64 v39, v39, v156, s[44:45]
	v_cndmask_b32_e64 v37, v156, v37, s[44:45]
	v_cndmask_b32_e64 v145, v40, v41, s[42:43]
	v_cndmask_b32_e64 v147, v42, v43, s[42:43]
	s_nop 1
	v_mov_b32_dpp v146, v145 quad_perm:[1,0,3,2] row_mask:0xf bank_mask:0xf
	v_mov_b32_dpp v156, v147 quad_perm:[1,0,3,2] row_mask:0xf bank_mask:0xf
	v_cndmask_b32_e64 v41, v41, v146, s[42:43]
	v_cndmask_b32_e64 v40, v146, v40, s[42:43]
	v_cndmask_b32_e64 v43, v43, v156, s[42:43]
	v_cndmask_b32_e64 v42, v156, v42, s[42:43]
	v_cndmask_b32_e64 v145, v40, v42, s[44:45]
	v_cndmask_b32_e64 v147, v41, v43, s[44:45]
	s_nop 1
	v_mov_b32_dpp v146, v145 quad_perm:[2,3,0,1] row_mask:0xf bank_mask:0xf
	v_mov_b32_dpp v156, v147 quad_perm:[2,3,0,1] row_mask:0xf bank_mask:0xf
	v_cndmask_b32_e64 v42, v42, v146, s[44:45]
	v_cndmask_b32_e64 v40, v146, v40, s[44:45]
	v_cndmask_b32_e64 v43, v43, v156, s[44:45]
	v_cndmask_b32_e64 v41, v156, v41, s[44:45]
; #define LAS __attribute__((address_space(3)))
; __device__ __forceinline__ unsigned pk2(float lo, float hi) { const f32x2_t_ v = {lo, hi}; return __builtin_bit_cast(unsigned, __builtin_convertvector(v, bf16x2_t_)); }
; __device__ __forceinline__ void hg_chunk(const LAS unsigned char* sl, f32x4 (&S)[8], float* Orow, int nvalid, int vs, int lane) {
;     const int r = lane & 15, q = lane >> 4;
;     const bf16x8 vfr = *(const LAS bf16x8*)(sl + 16384 + ((vs * 64 + lane) << 4));
;     f32x4 o0 = {0.f, 0.f, 0.f, 0.f}, o1 = {0.f, 0.f, 0.f, 0.f};
;     { const bf16x8 s0 = *(const LAS bf16x8*)(sl + 24576 + (lane << 4)), s1 = *(const LAS bf16x8*)(sl + 24576 + ((64 + lane) << 4));
;       o0 = __builtin_amdgcn_mfma_f32_16x16x32_bf16(s0, vfr, o0, 0, 0, 0); o1 = __builtin_amdgcn_mfma_f32_16x16x32_bf16(s1, vfr, o1, 0, 0, 0); }
; #pragma unroll
;     for (int m = 0; m < 4; ++m) {
;         v4u sw; sw.x = pk2(S[2 * m][0], S[2 * m][1]); sw.y = pk2(S[2 * m][2], S[2 * m][3]); sw.z = pk2(S[2 * m + 1][0], S[2 * m + 1][1]); sw.w = pk2(S[2 * m + 1][2], S[2 * m + 1][3]);
;         const bf16x8 sb = __builtin_bit_cast(bf16x8, sw);
;         const bf16x8 a0 = *(const LAS bf16x8*)(sl + ((m * 64 + lane) << 4)), a1 = *(const LAS bf16x8*)(sl + (((4 + m) * 64 + lane) << 4));
; __device__ __forceinline__ void hg_seq(const Frame& F, unsigned char* ws, const float* s0, float* sout, float* Og, int seq, bool sample, int vs_base, int nvs) {
;     ...
;     if (sample && active) {
; #pragma unroll
;         for (int kb = 0; kb < 8; ++kb)
; #pragma unroll
;             for (int i = 0; i < 4; ++i) S[kb][i] = s0[((size_t)seq * 128 + 16 * kb + 4 * q + i) * 128 + 16 * vs + r];
;     } else {
	v_cndmask_b32_e64 v145, v44, v45, s[42:43]
	v_cndmask_b32_e64 v147, v46, v47, s[42:43]
	s_nop 1
	v_mov_b32_dpp v146, v145 quad_perm:[1,0,3,2] row_mask:0xf bank_mask:0xf
	v_mov_b32_dpp v156, v147 quad_perm:[1,0,3,2] row_mask:0xf bank_mask:0xf
	v_cndmask_b32_e64 v45, v45, v146, s[42:43]
	v_cndmask_b32_e64 v44, v146, v44, s[42:43]
	v_cndmask_b32_e64 v47, v47, v156, s[42:43]
	v_cndmask_b32_e64 v46, v156, v46, s[42:43]
	v_cndmask_b32_e64 v145, v44, v46, s[44:45]
	v_cndmask_b32_e64 v147, v45, v47, s[44:45]
	s_nop 1
	v_mov_b32_dpp v146, v145 quad_perm:[2,3,0,1] row_mask:0xf bank_mask:0xf
	v_mov_b32_dpp v156, v147 quad_perm:[2,3,0,1] row_mask:0xf bank_mask:0xf
	v_cndmask_b32_e64 v46, v46, v146, s[44:45]
	v_cndmask_b32_e64 v44, v146, v44, s[44:45]
	v_cndmask_b32_e64 v47, v47, v156, s[44:45]
	v_cndmask_b32_e64 v45, v156, v45, s[44:45]
	v_cndmask_b32_e64 v145, v48, v49, s[42:43]
	v_cndmask_b32_e64 v147, v50, v51, s[42:43]
	s_nop 1
	v_mov_b32_dpp v146, v145 quad_perm:[1,0,3,2] row_mask:0xf bank_mask:0xf
	v_mov_b32_dpp v156, v147 quad_perm:[1,0,3,2] row_mask:0xf bank_mask:0xf
	v_cndmask_b32_e64 v49, v49, v146, s[42:43]
	v_cndmask_b32_e64 v48, v146, v48, s[42:43]
	v_cndmask_b32_e64 v51, v51, v156, s[42:43]
	v_cndmask_b32_e64 v50, v156, v50, s[42:43]
	v_cndmask_b32_e64 v145, v48, v50, s[44:45]
	v_cndmask_b32_e64 v147, v49, v51, s[44:45]
	s_nop 1
	v_mov_b32_dpp v146, v145 quad_perm:[2,3,0,1] row_mask:0xf bank_mask:0xf
	v_mov_b32_dpp v156, v147 quad_perm:[2,3,0,1] row_mask:0xf bank_mask:0xf
	v_cndmask_b32_e64 v50, v50, v146, s[44:45]
	v_cndmask_b32_e64 v48, v146, v48, s[44:45]
	v_cndmask_b32_e64 v51, v51, v156, s[44:45]
	v_cndmask_b32_e64 v49, v156, v49, s[44:45]
	v_cndmask_b32_e64 v145, v52, v53, s[42:43]
	v_cndmask_b32_e64 v147, v54, v55, s[42:43]
	s_nop 1
	v_mov_b32_dpp v146, v145 quad_perm:[1,0,3,2] row_mask:0xf bank_mask:0xf
	v_mov_b32_dpp v156, v147 quad_perm:[1,0,3,2] row_mask:0xf bank_mask:0xf
	v_cndmask_b32_e64 v53, v53, v146, s[42:43]
	v_cndmask_b32_e64 v52, v146, v52, s[42:43]
	v_cndmask_b32_e64 v55, v55, v156, s[42:43]
	v_cndmask_b32_e64 v54, v156, v54, s[42:43]
	v_cndmask_b32_e64 v145, v52, v54, s[44:45]
	v_cndmask_b32_e64 v147, v53, v55, s[44:45]
	s_nop 1
	v_mov_b32_dpp v146, v145 quad_perm:[2,3,0,1] row_mask:0xf bank_mask:0xf
	v_mov_b32_dpp v156, v147 quad_perm:[2,3,0,1] row_mask:0xf bank_mask:0xf
	v_cndmask_b32_e64 v54, v54, v146, s[44:45]
	v_cndmask_b32_e64 v52, v146, v52, s[44:45]
	v_cndmask_b32_e64 v55, v55, v156, s[44:45]
	v_cndmask_b32_e64 v53, v156, v53, s[44:45]
	v_cndmask_b32_e64 v145, v56, v57, s[42:43]
	v_cndmask_b32_e64 v147, v58, v59, s[42:43]
	s_nop 1
	v_mov_b32_dpp v146, v145 quad_perm:[1,0,3,2] row_mask:0xf bank_mask:0xf
	v_mov_b32_dpp v156, v147 quad_perm:[1,0,3,2] row_mask:0xf bank_mask:0xf
	v_cndmask_b32_e64 v57, v57, v146, s[42:43]
	v_cndmask_b32_e64 v56, v146, v56, s[42:43]
	v_cndmask_b32_e64 v59, v59, v156, s[42:43]
	v_cndmask_b32_e64 v58, v156, v58, s[42:43]
	v_cndmask_b32_e64 v145, v56, v58, s[44:45]
	v_cndmask_b32_e64 v147, v57, v59, s[44:45]
	s_nop 1
	v_mov_b32_dpp v146, v145 quad_perm:[2,3,0,1] row_mask:0xf bank_mask:0xf
	v_mov_b32_dpp v156, v147 quad_perm:[2,3,0,1] row_mask:0xf bank_mask:0xf
	v_cndmask_b32_e64 v58, v58, v146, s[44:45]
	v_cndmask_b32_e64 v56, v146, v56, s[44:45]
	v_cndmask_b32_e64 v59, v59, v156, s[44:45]
	v_cndmask_b32_e64 v57, v156, v57, s[44:45]
	v_cndmask_b32_e64 v145, v60, v61, s[42:43]
	v_cndmask_b32_e64 v147, v62, v63, s[42:43]
	s_nop 1
	v_mov_b32_dpp v146, v145 quad_perm:[1,0,3,2] row_mask:0xf bank_mask:0xf
	v_mov_b32_dpp v156, v147 quad_perm:[1,0,3,2] row_mask:0xf bank_mask:0xf
	v_cndmask_b32_e64 v61, v61, v146, s[42:43]
	v_cndmask_b32_e64 v60, v146, v60, s[42:43]
	v_cndmask_b32_e64 v63, v63, v156, s[42:43]
	v_cndmask_b32_e64 v62, v156, v62, s[42:43]
	v_cndmask_b32_e64 v145, v60, v62, s[44:45]
	v_cndmask_b32_e64 v147, v61, v63, s[44:45]
	s_nop 1
	v_mov_b32_dpp v146, v145 quad_perm:[2,3,0,1] row_mask:0xf bank_mask:0xf
	v_mov_b32_dpp v156, v147 quad_perm:[2,3,0,1] row_mask:0xf bank_mask:0xf
	v_cndmask_b32_e64 v62, v62, v146, s[44:45]
	v_cndmask_b32_e64 v60, v146, v60, s[44:45]
	v_cndmask_b32_e64 v63, v63, v156, s[44:45]
	v_cndmask_b32_e64 v61, v156, v61, s[44:45]
	v_cndmask_b32_e64 v145, v64, v65, s[42:43]
	v_cndmask_b32_e64 v147, v66, v67, s[42:43]
	s_nop 1
	v_mov_b32_dpp v146, v145 quad_perm:[1,0,3,2] row_mask:0xf bank_mask:0xf
	v_mov_b32_dpp v156, v147 quad_perm:[1,0,3,2] row_mask:0xf bank_mask:0xf
	v_cndmask_b32_e64 v65, v65, v146, s[42:43]
	v_cndmask_b32_e64 v64, v146, v64, s[42:43]
	v_cndmask_b32_e64 v67, v67, v156, s[42:43]
	v_cndmask_b32_e64 v66, v156, v66, s[42:43]
	v_cndmask_b32_e64 v145, v64, v66, s[44:45]
	v_cndmask_b32_e64 v147, v65, v67, s[44:45]
	s_nop 1
	v_mov_b32_dpp v146, v145 quad_perm:[2,3,0,1] row_mask:0xf bank_mask:0xf
	v_mov_b32_dpp v156, v147 quad_perm:[2,3,0,1] row_mask:0xf bank_mask:0xf
	v_cndmask_b32_e64 v66, v66, v146, s[44:45]
	v_cndmask_b32_e64 v64, v146, v64, s[44:45]
	v_cndmask_b32_e64 v67, v67, v156, s[44:45]
	v_cndmask_b32_e64 v65, v156, v65, s[44:45]
	v_add_u32_e32 v1, 0x6c00, v142
	v_add_u32_e32 v2, 0x6c00, v143
	v_add_u32_e32 v3, 0x6c00, v144
	ds_read_b128 v[164:167], v3 offset:26624
	ds_read_b128 v[168:171], v3 offset:26688
	ds_read_b128 v[172:175], v3 offset:26752
	ds_read_b128 v[176:179], v3 offset:26816
	ds_read_b128 v[180:183], v3 offset:26880
	ds_read_b128 v[184:187], v3 offset:26944
	ds_read_b128 v[148:151], v3 offset:27008
	ds_read_b128 v[152:155], v3 offset:27072
	ds_read_b128 v[84:87], v2 offset:16384
	ds_read_b128 v[88:91], v1 offset:24576
	ds_read_b128 v[92:95], v1 offset:0
	ds_read_b128 v[96:99], v1 offset:1024
	ds_read_b128 v[100:103], v1 offset:2048
	ds_read_b128 v[104:107], v1 offset:3072
	v_cvt_pk_bf16_f32 v68, v36, v37
	v_cvt_pk_bf16_f32 v69, v38, v39
	v_cvt_pk_bf16_f32 v70, v40, v41
	v_cvt_pk_bf16_f32 v71, v42, v43
	v_cvt_pk_bf16_f32 v72, v44, v45
	v_cvt_pk_bf16_f32 v73, v46, v47
	v_cvt_pk_bf16_f32 v74, v48, v49
	v_cvt_pk_bf16_f32 v75, v50, v51
	v_cvt_pk_bf16_f32 v76, v52, v53
	v_cvt_pk_bf16_f32 v77, v54, v55
	v_cvt_pk_bf16_f32 v78, v56, v57
	v_cvt_pk_bf16_f32 v79, v58, v59
	v_cvt_pk_bf16_f32 v80, v60, v61
	v_cvt_pk_bf16_f32 v81, v62, v63
	v_cvt_pk_bf16_f32 v82, v64, v65
	v_cvt_pk_bf16_f32 v83, v66, v67
	s_waitcnt lgkmcnt(6)
; #define LAS __attribute__((address_space(3)))
; __device__ __forceinline__ unsigned pk2(float lo, float hi) { const f32x2_t_ v = {lo, hi}; return __builtin_bit_cast(unsigned, __builtin_convertvector(v, bf16x2_t_)); }
; __device__ __forceinline__ void hg_chunk(const LAS unsigned char* sl, f32x4 (&S)[8], float* Orow, int nvalid, int vs, int lane) {
;     const int r = lane & 15, q = lane >> 4;
;     const bf16x8 vfr = *(const LAS bf16x8*)(sl + 16384 + ((vs * 64 + lane) << 4));
;     f32x4 o0 = {0.f, 0.f, 0.f, 0.f}, o1 = {0.f, 0.f, 0.f, 0.f};
;     { const bf16x8 s0 = *(const LAS bf16x8*)(sl + 24576 + (lane << 4)), s1 = *(const LAS bf16x8*)(sl + 24576 + ((64 + lane) << 4));
;       o0 = __builtin_amdgcn_mfma_f32_16x16x32_bf16(s0, vfr, o0, 0, 0, 0); o1 = __builtin_amdgcn_mfma_f32_16x16x32_bf16(s1, vfr, o1, 0, 0, 0); }
; #pragma unroll
;     for (int m = 0; m < 4; ++m) {
;         v4u sw; sw.x = pk2(S[2 * m][0], S[2 * m][1]); sw.y = pk2(S[2 * m][2], S[2 * m][3]); sw.z = pk2(S[2 * m + 1][0], S[2 * m + 1][1]); sw.w = pk2(S[2 * m + 1][2], S[2 * m + 1][3]);
;         const bf16x8 sb = __builtin_bit_cast(bf16x8, sw);
;         const bf16x8 a0 = *(const LAS bf16x8*)(sl + ((m * 64 + lane) << 4)), a1 = *(const LAS bf16x8*)(sl + (((4 + m) * 64 + lane) << 4));
;         o0 = __builtin_amdgcn_mfma_f32_16x16x32_bf16(a0, sb, o0, 0, 0, 0); o1 = __builtin_amdgcn_mfma_f32_16x16x32_bf16(a1, sb, o1, 0, 0, 0);
;     }
; #pragma unroll
;     for (int i = 0; i < 4; ++i) { const int c0 = 4 * q + i;
;         if (c0 < nvalid) Orow[(size_t)c0 * DA + 16 * vs + r] = o0[i];
;         if (c0 + 16 < nvalid) Orow[(size_t)(c0 + 16) * DA + 16 * vs + r] = o1[i]; }
; #pragma unroll
;     for (int kb = 0; kb < 8; ++kb) { const f32x4 d = *(const LAS f32x4*)(sl + 26624 + ((16 * kb + 4 * q) << 2));
;         const bf16x8 ke = *(const LAS bf16x8*)(sl + 8192 + ((kb * 64 + lane) << 4));
;         S[kb] = __builtin_amdgcn_mfma_f32_16x16x32_bf16(ke, vfr, S[kb] * d, 0, 0, 0); }
	v_pk_mul_f32 v[36:37], v[36:37], v[164:165]
	v_pk_mul_f32 v[38:39], v[38:39], v[166:167]
	v_pk_mul_f32 v[40:41], v[40:41], v[168:169]
	v_pk_mul_f32 v[42:43], v[42:43], v[170:171]
	v_pk_mul_f32 v[44:45], v[44:45], v[172:173]
	v_pk_mul_f32 v[46:47], v[46:47], v[174:175]
	v_pk_mul_f32 v[48:49], v[48:49], v[176:177]
	v_pk_mul_f32 v[50:51], v[50:51], v[178:179]
	v_pk_mul_f32 v[52:53], v[52:53], v[180:181]
	v_pk_mul_f32 v[54:55], v[54:55], v[182:183]
	v_pk_mul_f32 v[56:57], v[56:57], v[184:185]
	v_pk_mul_f32 v[58:59], v[58:59], v[186:187]
	v_pk_mul_f32 v[60:61], v[60:61], v[148:149]
	v_pk_mul_f32 v[62:63], v[62:63], v[150:151]
	v_pk_mul_f32 v[64:65], v[64:65], v[152:153]
	v_pk_mul_f32 v[66:67], v[66:67], v[154:155]
	ds_read_b128 v[108:111], v1 offset:8192
	ds_read_b128 v[112:115], v1 offset:9216
	ds_read_b128 v[116:119], v1 offset:10240
	ds_read_b128 v[120:123], v1 offset:11264
	ds_read_b128 v[124:127], v1 offset:12288
	ds_read_b128 v[128:131], v1 offset:13312
	ds_read_b128 v[132:135], v1 offset:14336
	ds_read_b128 v[136:139], v1 offset:15360
	s_waitcnt lgkmcnt(12)
	v_mfma_f32_16x16x32_bf16 v[196:199], v[88:91], v[84:87], 0
	s_waitcnt lgkmcnt(11)
	v_mfma_f32_16x16x32_bf16 v[196:199], v[92:95], v[68:71], v[196:199]
	s_waitcnt lgkmcnt(10)
	v_mfma_f32_16x16x32_bf16 v[196:199], v[96:99], v[72:75], v[196:199]
	s_waitcnt lgkmcnt(9)
	v_mfma_f32_16x16x32_bf16 v[196:199], v[100:103], v[76:79], v[196:199]
	s_waitcnt lgkmcnt(8)
	v_mfma_f32_16x16x32_bf16 v[196:199], v[104:107], v[80:83], v[196:199]
	s_waitcnt lgkmcnt(7)
	v_mfma_f32_16x16x32_bf16 v[36:39], v[108:111], v[84:87], v[36:39]
	s_waitcnt lgkmcnt(6)
	v_mfma_f32_16x16x32_bf16 v[40:43], v[112:115], v[84:87], v[40:43]
	s_waitcnt lgkmcnt(5)
	v_mfma_f32_16x16x32_bf16 v[44:47], v[116:119], v[84:87], v[44:47]
	s_waitcnt lgkmcnt(4)
	v_mfma_f32_16x16x32_bf16 v[48:51], v[120:123], v[84:87], v[48:51]
	s_waitcnt lgkmcnt(3)
	v_mfma_f32_16x16x32_bf16 v[52:55], v[124:127], v[84:87], v[52:55]
	s_waitcnt lgkmcnt(2)
	v_mfma_f32_16x16x32_bf16 v[56:59], v[128:131], v[84:87], v[56:59]
	s_waitcnt lgkmcnt(1)
	v_mfma_f32_16x16x32_bf16 v[60:63], v[132:135], v[84:87], v[60:63]
	s_waitcnt lgkmcnt(0)
	v_mfma_f32_16x16x32_bf16 v[64:67], v[136:139], v[84:87], v[64:67]
	s_mov_b32 exec_hi, 0
	global_store_dword v208, v196, s[12:13]
	global_store_dword v208, v197, s[12:13] offset:2048
	global_store_dword v209, v198, s[12:13]
	global_store_dword v209, v199, s[12:13] offset:2048
	s_mov_b64 exec, -1
	s_add_u32 s12, s12, 0x80000
	s_addc_u32 s13, s13, 0
	s_nop 7
	v_cndmask_b32_e64 v145, v36, v37, s[42:43]
	v_cndmask_b32_e64 v147, v38, v39, s[42:43]
	s_nop 1
	v_mov_b32_dpp v146, v145 quad_perm:[1,0,3,2] row_mask:0xf bank_mask:0xf
	v_mov_b32_dpp v156, v147 quad_perm:[1,0,3,2] row_mask:0xf bank_mask:0xf
	v_cndmask_b32_e64 v37, v37, v146, s[42:43]
	v_cndmask_b32_e64 v36, v146, v36, s[42:43]
	v_cndmask_b32_e64 v39, v39, v156, s[42:43]
	v_cndmask_b32_e64 v38, v156, v38, s[42:43]
	v_cndmask_b32_e64 v145, v36, v38, s[44:45]
	v_cndmask_b32_e64 v147, v37, v39, s[44:45]
	s_nop 1
	v_mov_b32_dpp v146, v145 quad_perm:[2,3,0,1] row_mask:0xf bank_mask:0xf
	v_mov_b32_dpp v156, v147 quad_perm:[2,3,0,1] row_mask:0xf bank_mask:0xf
	v_cndmask_b32_e64 v38, v38, v146, s[44:45]
	v_cndmask_b32_e64 v36, v146, v36, s[44:45]
	v_cndmask_b32_e64 v39, v39, v156, s[44:45]
	v_cndmask_b32_e64 v37, v156, v37, s[44:45]
	v_cndmask_b32_e64 v145, v40, v41, s[42:43]
	v_cndmask_b32_e64 v147, v42, v43, s[42:43]
	s_nop 1
	v_mov_b32_dpp v146, v145 quad_perm:[1,0,3,2] row_mask:0xf bank_mask:0xf
	v_mov_b32_dpp v156, v147 quad_perm:[1,0,3,2] row_mask:0xf bank_mask:0xf
	v_cndmask_b32_e64 v41, v41, v146, s[42:43]
	v_cndmask_b32_e64 v40, v146, v40, s[42:43]
	v_cndmask_b32_e64 v43, v43, v156, s[42:43]
	v_cndmask_b32_e64 v42, v156, v42, s[42:43]
	v_cndmask_b32_e64 v145, v40, v42, s[44:45]
	v_cndmask_b32_e64 v147, v41, v43, s[44:45]
	s_nop 1
	v_mov_b32_dpp v146, v145 quad_perm:[2,3,0,1] row_mask:0xf bank_mask:0xf
	v_mov_b32_dpp v156, v147 quad_perm:[2,3,0,1] row_mask:0xf bank_mask:0xf
	v_cndmask_b32_e64 v42, v42, v146, s[44:45]
	v_cndmask_b32_e64 v40, v146, v40, s[44:45]
	v_cndmask_b32_e64 v43, v43, v156, s[44:45]
	v_cndmask_b32_e64 v41, v156, v41, s[44:45]
	v_cndmask_b32_e64 v145, v44, v45, s[42:43]
	v_cndmask_b32_e64 v147, v46, v47, s[42:43]
	s_nop 1
	v_mov_b32_dpp v146, v145 quad_perm:[1,0,3,2] row_mask:0xf bank_mask:0xf
	v_mov_b32_dpp v156, v147 quad_perm:[1,0,3,2] row_mask:0xf bank_mask:0xf
	v_cndmask_b32_e64 v45, v45, v146, s[42:43]
	v_cndmask_b32_e64 v44, v146, v44, s[42:43]
	v_cndmask_b32_e64 v47, v47, v156, s[42:43]
	v_cndmask_b32_e64 v46, v156, v46, s[42:43]
	v_cndmask_b32_e64 v145, v44, v46, s[44:45]
	v_cndmask_b32_e64 v147, v45, v47, s[44:45]
	s_nop 1
	v_mov_b32_dpp v146, v145 quad_perm:[2,3,0,1] row_mask:0xf bank_mask:0xf
	v_mov_b32_dpp v156, v147 quad_perm:[2,3,0,1] row_mask:0xf bank_mask:0xf
; #define LDSBAR() do { asm volatile("s_waitcnt lgkmcnt(0)" ::: "memory"); __builtin_amdgcn_s_barrier(); asm volatile("" ::: "memory"); } while (0)
; __device__ __forceinline__ const float* kin(int k) { KArgs p = (KArgs)__builtin_amdgcn_kernarg_segment_ptr(); asm volatile("" : "+s"(p)); return p->in[k]; }
; __device__ __forceinline__ void hg_seq(const Frame& F, unsigned char* ws, const float* s0, float* sout, float* Og, int seq, bool sample, int vs_base, int nvs) {
;     ...
;     if (active) {
; #pragma unroll
;     for (int kb = 0; kb < 8; ++kb)
; #pragma unroll
;         for (int i = 0; i < 4; ++i) sout[((size_t)seq * 128 + 16 * kb + 4 * q + i) * 128 + 16 * vs + r] = S[kb][i];
;     }
;     LDSBAR();
; __global__ void __launch_bounds__(NWAVES * 64, 2) mk_fwd(Args args) {
;     ...
;                 const int cgw = (bid - NSCAN) * NWAVES + F.wave, CNGW = (G - NSCAN) * NWAVES;
;                 zb_rows(ws, kin(11), st_c, out, F.lane, cgw, CNGW);
;                 conv_mat(kin(13), nullptr, DM, DA, DM, (bf16*)(ws + WS_WA), 0, 0, SCR_, F.lane, cgw, CNGW);
;                 conv_mat(kin(14), nullptr, DM, DA, DM, (bf16*)(ws + WS_WB), 0, 0, SCR_, F.lane, (cgw + CNGW / 4) % CNGW, CNGW);
;                 conv_mat(kin(15), nullptr, DM, DM, DM, (bf16*)(ws + WS_WO), 0, 0, SCR_, F.lane, (cgw + CNGW / 2) % CNGW, CNGW);
	v_cndmask_b32_e64 v46, v46, v146, s[44:45]
	v_cndmask_b32_e64 v44, v146, v44, s[44:45]
	v_cndmask_b32_e64 v47, v47, v156, s[44:45]
	v_cndmask_b32_e64 v45, v156, v45, s[44:45]
	v_cndmask_b32_e64 v145, v48, v49, s[42:43]
	v_cndmask_b32_e64 v147, v50, v51, s[42:43]
	s_nop 1
	v_mov_b32_dpp v146, v145 quad_perm:[1,0,3,2] row_mask:0xf bank_mask:0xf
	v_mov_b32_dpp v156, v147 quad_perm:[1,0,3,2] row_mask:0xf bank_mask:0xf
	v_cndmask_b32_e64 v49, v49, v146, s[42:43]
	v_cndmask_b32_e64 v48, v146, v48, s[42:43]
	v_cndmask_b32_e64 v51, v51, v156, s[42:43]
	v_cndmask_b32_e64 v50, v156, v50, s[42:43]
	v_cndmask_b32_e64 v145, v48, v50, s[44:45]
	v_cndmask_b32_e64 v147, v49, v51, s[44:45]
	s_nop 1
	v_mov_b32_dpp v146, v145 quad_perm:[2,3,0,1] row_mask:0xf bank_mask:0xf
	v_mov_b32_dpp v156, v147 quad_perm:[2,3,0,1] row_mask:0xf bank_mask:0xf
	v_cndmask_b32_e64 v50, v50, v146, s[44:45]
	v_cndmask_b32_e64 v48, v146, v48, s[44:45]
	v_cndmask_b32_e64 v51, v51, v156, s[44:45]
	v_cndmask_b32_e64 v49, v156, v49, s[44:45]
	v_cndmask_b32_e64 v145, v52, v53, s[42:43]
	v_cndmask_b32_e64 v147, v54, v55, s[42:43]
	s_nop 1
	v_mov_b32_dpp v146, v145 quad_perm:[1,0,3,2] row_mask:0xf bank_mask:0xf
	v_mov_b32_dpp v156, v147 quad_perm:[1,0,3,2] row_mask:0xf bank_mask:0xf
	v_cndmask_b32_e64 v53, v53, v146, s[42:43]
	v_cndmask_b32_e64 v52, v146, v52, s[42:43]
	v_cndmask_b32_e64 v55, v55, v156, s[42:43]
	v_cndmask_b32_e64 v54, v156, v54, s[42:43]
	v_cndmask_b32_e64 v145, v52, v54, s[44:45]
	v_cndmask_b32_e64 v147, v53, v55, s[44:45]
	s_nop 1
	v_mov_b32_dpp v146, v145 quad_perm:[2,3,0,1] row_mask:0xf bank_mask:0xf
	v_mov_b32_dpp v156, v147 quad_perm:[2,3,0,1] row_mask:0xf bank_mask:0xf
	v_cndmask_b32_e64 v54, v54, v146, s[44:45]
	v_cndmask_b32_e64 v52, v146, v52, s[44:45]
	v_cndmask_b32_e64 v55, v55, v156, s[44:45]
	v_cndmask_b32_e64 v53, v156, v53, s[44:45]
	v_cndmask_b32_e64 v145, v56, v57, s[42:43]
	v_cndmask_b32_e64 v147, v58, v59, s[42:43]
	s_nop 1
	v_mov_b32_dpp v146, v145 quad_perm:[1,0,3,2] row_mask:0xf bank_mask:0xf
	v_mov_b32_dpp v156, v147 quad_perm:[1,0,3,2] row_mask:0xf bank_mask:0xf
	v_cndmask_b32_e64 v57, v57, v146, s[42:43]
	v_cndmask_b32_e64 v56, v146, v56, s[42:43]
	v_cndmask_b32_e64 v59, v59, v156, s[42:43]
	v_cndmask_b32_e64 v58, v156, v58, s[42:43]
	v_cndmask_b32_e64 v145, v56, v58, s[44:45]
	v_cndmask_b32_e64 v147, v57, v59, s[44:45]
	s_nop 1
	v_mov_b32_dpp v146, v145 quad_perm:[2,3,0,1] row_mask:0xf bank_mask:0xf
	v_mov_b32_dpp v156, v147 quad_perm:[2,3,0,1] row_mask:0xf bank_mask:0xf
	v_cndmask_b32_e64 v58, v58, v146, s[44:45]
	v_cndmask_b32_e64 v56, v146, v56, s[44:45]
	v_cndmask_b32_e64 v59, v59, v156, s[44:45]
	v_cndmask_b32_e64 v57, v156, v57, s[44:45]
	v_cndmask_b32_e64 v145, v60, v61, s[42:43]
	v_cndmask_b32_e64 v147, v62, v63, s[42:43]
	s_nop 1
	v_mov_b32_dpp v146, v145 quad_perm:[1,0,3,2] row_mask:0xf bank_mask:0xf
	v_mov_b32_dpp v156, v147 quad_perm:[1,0,3,2] row_mask:0xf bank_mask:0xf
	v_cndmask_b32_e64 v61, v61, v146, s[42:43]
	v_cndmask_b32_e64 v60, v146, v60, s[42:43]
	v_cndmask_b32_e64 v63, v63, v156, s[42:43]
	v_cndmask_b32_e64 v62, v156, v62, s[42:43]
	v_cndmask_b32_e64 v145, v60, v62, s[44:45]
	v_cndmask_b32_e64 v147, v61, v63, s[44:45]
	s_nop 1
	v_mov_b32_dpp v146, v145 quad_perm:[2,3,0,1] row_mask:0xf bank_mask:0xf
	v_mov_b32_dpp v156, v147 quad_perm:[2,3,0,1] row_mask:0xf bank_mask:0xf
	v_cndmask_b32_e64 v62, v62, v146, s[44:45]
	v_cndmask_b32_e64 v60, v146, v60, s[44:45]
	v_cndmask_b32_e64 v63, v63, v156, s[44:45]
	v_cndmask_b32_e64 v61, v156, v61, s[44:45]
	v_cndmask_b32_e64 v145, v64, v65, s[42:43]
	v_cndmask_b32_e64 v147, v66, v67, s[42:43]
	s_nop 1
	v_mov_b32_dpp v146, v145 quad_perm:[1,0,3,2] row_mask:0xf bank_mask:0xf
	v_mov_b32_dpp v156, v147 quad_perm:[1,0,3,2] row_mask:0xf bank_mask:0xf
	v_cndmask_b32_e64 v65, v65, v146, s[42:43]
	v_cndmask_b32_e64 v64, v146, v64, s[42:43]
	v_cndmask_b32_e64 v67, v67, v156, s[42:43]
	v_cndmask_b32_e64 v66, v156, v66, s[42:43]
	v_cndmask_b32_e64 v145, v64, v66, s[44:45]
	v_cndmask_b32_e64 v147, v65, v67, s[44:45]
	s_nop 1
	v_mov_b32_dpp v146, v145 quad_perm:[2,3,0,1] row_mask:0xf bank_mask:0xf
	v_mov_b32_dpp v156, v147 quad_perm:[2,3,0,1] row_mask:0xf bank_mask:0xf
	v_cndmask_b32_e64 v66, v66, v146, s[44:45]
	v_cndmask_b32_e64 v64, v146, v64, s[44:45]
	v_cndmask_b32_e64 v67, v67, v156, s[44:45]
	v_cndmask_b32_e64 v65, v156, v65, s[44:45]
	global_store_dwordx4 v200, v[36:39], s[10:11]
	global_store_dwordx4 v201, v[40:43], s[10:11]
	global_store_dwordx4 v202, v[44:47], s[10:11]
	global_store_dwordx4 v203, v[48:51], s[10:11]
	global_store_dwordx4 v204, v[52:55], s[10:11]
	global_store_dwordx4 v205, v[56:59], s[10:11]
	global_store_dwordx4 v206, v[60:63], s[10:11]
	global_store_dwordx4 v207, v[64:67], s[10:11]
	s_add_u32 s10, s10, s34
	s_addc_u32 s11, s11, 0
	s_waitcnt lgkmcnt(0)
	s_barrier
	s_mov_b64 s[6:7], 0
